# sample-row prepass (k1,k5,k8,k12): W LDS-DMA pieces issued first, A fragments in K order, first K half computed while second half of A is in flight
# speedup vs baseline: 1.0076x; 1.0076x over previous
.Linp1_qok:
	s_cmp_gt_u32 s29, 23
	s_cbranch_scc1 .Linp1_next
	s_add_u32 s20, s16, 0x5100000
	s_addc_u32 s21, s17, 0
	s_add_u32 s22, s16, 0x100000
	s_addc_u32 s23, s17, 0
	s_add_u32 s24, s16, 0xd400000
	s_addc_u32 s25, s17, 0
	s_and_b32 s28, s12, 7
	s_lshl_b32 s29, s29, 1
	s_add_u32 s29, s29, s6
	s_lshr_b32 s30, s29, 3
	s_mul_i32 s28, s28, 6
	s_add_u32 s30, s30, s28
	s_and_b32 s31, s29, 7
	s_lshl_b32 s33, s31, 17
	s_lshl_b32 s34, s30, 17
	v_lshlrev_b32_e32 v215, 11, v202
	v_lshl_add_u32 v215, v203, 4, v215
	v_add_u32_e32 v194, s33, v204
	v_add_u32_e32 v198, s34, v215
	v_add_u32_e32 v195, s33, v204
	v_add_u32_e32 v199, s34, v215
	v_add_u32_e32 v196, s33, v204
	v_add_u32_e32 v200, s34, v215
	v_add_u32_e32 v197, s33, v204
	v_add_u32_e32 v201, s34, v215
	v_add_u32_e32 v195, 0x8000, v195
	v_add_u32_e32 v199, 0x8000, v199
	v_add_u32_e32 v196, 0x10000, v196
	v_add_u32_e32 v200, 0x10000, v200
	v_add_u32_e32 v197, 0x18000, v197
	v_add_u32_e32 v201, 0x18000, v201
	s_mul_i32 s33, s31, 0x60000
	s_lshl_b32 s34, s30, 7
	s_add_u32 s33, s33, s34
	v_add_u32_e32 v211, s33, v209
	s_lshr_b32 s35, s30, 3
	s_and_b32 s36, s30, 7
	s_lshl_b32 s36, s36, 8
	s_mov_b32 s37, 0x3f800000
	s_mov_b32 s42, 1
	s_cmp_eq_u32 s35, 0
	s_cselect_b32 s37, 0x3e38aa3b, s37
	s_cselect_b32 s42, 0, s42
	s_cmp_eq_u32 s35, 3
	s_cselect_b32 s37, 0x3e38aa3b, s37
	s_cselect_b32 s42, 0, s42
	s_sub_u32 s43, s35, 1
	s_cmp_gt_u32 s35, 3
	s_cselect_b32 s44, 1, 0
	s_sub_u32 s43, s43, s44
	s_lshl_b32 s43, s43, 20
	s_lshl_b32 s44, s31, 17
	s_add_u32 s43, s43, s44
	s_add_u32 s43, s43, s36
	s_add_u32 s38, s40, s43
	s_addc_u32 s39, s41, 0
	s_add_u32 s38, s38, 0xd280000
	s_addc_u32 s39, s39, 0
	s_lshl_b32 s44, s4, 8
	s_add_u32 s44, s22, s44
	s_addc_u32 s45, s23, 0
	s_lshl_b32 s46, s4, 14
	s_add_i32 m0, s46, 0x0
	s_nop 0
	global_load_lds_dwordx4 v198, s[44:45]
	s_add_i32 m0, s46, 0x400
	s_nop 0
	global_load_lds_dwordx4 v199, s[44:45]
	s_add_i32 m0, s46, 0x800
	s_nop 0
	global_load_lds_dwordx4 v200, s[44:45]
	s_add_i32 m0, s46, 0xc00
	s_nop 0
	global_load_lds_dwordx4 v201, s[44:45]
	s_add_u32 s44, s44, 64
	s_addc_u32 s45, s45, 0
	s_add_i32 m0, s46, 0x1000
	s_nop 0
	global_load_lds_dwordx4 v198, s[44:45]
	s_add_i32 m0, s46, 0x1400
	s_nop 0
	global_load_lds_dwordx4 v199, s[44:45]
	s_add_i32 m0, s46, 0x1800
	s_nop 0
	global_load_lds_dwordx4 v200, s[44:45]
	s_add_i32 m0, s46, 0x1c00
	s_nop 0
	global_load_lds_dwordx4 v201, s[44:45]
	s_add_u32 s44, s44, 64
	s_addc_u32 s45, s45, 0
	s_add_i32 m0, s46, 0x2000
	s_nop 0
	global_load_lds_dwordx4 v198, s[44:45]
	s_add_i32 m0, s46, 0x2400
	s_nop 0
	global_load_lds_dwordx4 v199, s[44:45]
	s_add_i32 m0, s46, 0x2800
	s_nop 0
	global_load_lds_dwordx4 v200, s[44:45]
	s_add_i32 m0, s46, 0x2c00
	s_nop 0
	global_load_lds_dwordx4 v201, s[44:45]
	s_add_u32 s44, s44, 64
	s_addc_u32 s45, s45, 0
	s_add_i32 m0, s46, 0x3000
	s_nop 0
	global_load_lds_dwordx4 v198, s[44:45]
	s_add_i32 m0, s46, 0x3400
	s_nop 0
	global_load_lds_dwordx4 v199, s[44:45]
	s_add_i32 m0, s46, 0x3800
	s_nop 0
	global_load_lds_dwordx4 v200, s[44:45]
	s_add_i32 m0, s46, 0x3c00
	s_nop 0
	global_load_lds_dwordx4 v201, s[44:45]
	global_load_dwordx4 v[66:69], v194, s[20:21] offset:0
	global_load_dwordx4 v[70:73], v195, s[20:21] offset:0
	global_load_dwordx4 v[74:77], v196, s[20:21] offset:0
	global_load_dwordx4 v[78:81], v197, s[20:21] offset:0
	global_load_dwordx4 v[82:85], v194, s[20:21] offset:64
	global_load_dwordx4 v[86:89], v195, s[20:21] offset:64
	global_load_dwordx4 v[90:93], v196, s[20:21] offset:64
	global_load_dwordx4 v[94:97], v197, s[20:21] offset:64
	global_load_dwordx4 v[98:101], v194, s[20:21] offset:128
	global_load_dwordx4 v[102:105], v195, s[20:21] offset:128
	global_load_dwordx4 v[106:109], v196, s[20:21] offset:128
	global_load_dwordx4 v[110:113], v197, s[20:21] offset:128
	global_load_dwordx4 v[114:117], v194, s[20:21] offset:192
	global_load_dwordx4 v[118:121], v195, s[20:21] offset:192
	global_load_dwordx4 v[122:125], v196, s[20:21] offset:192
	global_load_dwordx4 v[126:129], v197, s[20:21] offset:192
	global_load_dwordx4 v[130:133], v194, s[20:21] offset:256
	global_load_dwordx4 v[134:137], v195, s[20:21] offset:256
	global_load_dwordx4 v[138:141], v196, s[20:21] offset:256
	global_load_dwordx4 v[142:145], v197, s[20:21] offset:256
	global_load_dwordx4 v[146:149], v194, s[20:21] offset:320
	global_load_dwordx4 v[150:153], v195, s[20:21] offset:320
	global_load_dwordx4 v[154:157], v196, s[20:21] offset:320
	global_load_dwordx4 v[158:161], v197, s[20:21] offset:320
	global_load_dwordx4 v[162:165], v194, s[20:21] offset:384
	global_load_dwordx4 v[166:169], v195, s[20:21] offset:384
	global_load_dwordx4 v[170:173], v196, s[20:21] offset:384
	global_load_dwordx4 v[174:177], v197, s[20:21] offset:384
	global_load_dwordx4 v[178:181], v194, s[20:21] offset:448
	global_load_dwordx4 v[182:185], v195, s[20:21] offset:448
	global_load_dwordx4 v[186:189], v196, s[20:21] offset:448
	global_load_dwordx4 v[190:193], v197, s[20:21] offset:448
	s_waitcnt vmcnt(16)
	s_barrier
	s_lshl_b32 s47, s5, 15
	v_lshl_add_u32 v214, v205, 4, s47
	ds_read_b128 v[218:221], v214 offset:0
	ds_read_b128 v[222:225], v214 offset:1024
	ds_read_b128 v[226:229], v214 offset:2048
	ds_read_b128 v[230:233], v214 offset:3072
	ds_read_b128 v[234:237], v214 offset:4096
	ds_read_b128 v[238:241], v214 offset:5120
	ds_read_b128 v[242:245], v214 offset:6144
	ds_read_b128 v[246:249], v214 offset:7168
	s_waitcnt lgkmcnt(4)
	v_mfma_f32_16x16x32_bf16 v[2:5], v[218:221], v[66:69], 0
	v_mfma_f32_16x16x32_bf16 v[6:9], v[222:225], v[66:69], 0
	v_mfma_f32_16x16x32_bf16 v[10:13], v[226:229], v[66:69], 0
	v_mfma_f32_16x16x32_bf16 v[14:17], v[230:233], v[66:69], 0
	v_mfma_f32_16x16x32_bf16 v[18:21], v[218:221], v[70:73], 0
	v_mfma_f32_16x16x32_bf16 v[22:25], v[222:225], v[70:73], 0
	v_mfma_f32_16x16x32_bf16 v[26:29], v[226:229], v[70:73], 0
	v_mfma_f32_16x16x32_bf16 v[30:33], v[230:233], v[70:73], 0
	v_mfma_f32_16x16x32_bf16 v[34:37], v[218:221], v[74:77], 0
	v_mfma_f32_16x16x32_bf16 v[38:41], v[222:225], v[74:77], 0
	v_mfma_f32_16x16x32_bf16 v[42:45], v[226:229], v[74:77], 0
	v_mfma_f32_16x16x32_bf16 v[46:49], v[230:233], v[74:77], 0
	v_mfma_f32_16x16x32_bf16 v[50:53], v[218:221], v[78:81], 0
	v_mfma_f32_16x16x32_bf16 v[54:57], v[222:225], v[78:81], 0
	v_mfma_f32_16x16x32_bf16 v[58:61], v[226:229], v[78:81], 0
	v_mfma_f32_16x16x32_bf16 v[62:65], v[230:233], v[78:81], 0
	ds_read_b128 v[218:221], v214 offset:8192
	ds_read_b128 v[222:225], v214 offset:9216
	ds_read_b128 v[226:229], v214 offset:10240
	ds_read_b128 v[230:233], v214 offset:11264
	s_waitcnt lgkmcnt(4)
	v_mfma_f32_16x16x32_bf16 v[2:5], v[234:237], v[82:85], v[2:5]
	v_mfma_f32_16x16x32_bf16 v[6:9], v[238:241], v[82:85], v[6:9]
	v_mfma_f32_16x16x32_bf16 v[10:13], v[242:245], v[82:85], v[10:13]
	v_mfma_f32_16x16x32_bf16 v[14:17], v[246:249], v[82:85], v[14:17]
	v_mfma_f32_16x16x32_bf16 v[18:21], v[234:237], v[86:89], v[18:21]
	v_mfma_f32_16x16x32_bf16 v[22:25], v[238:241], v[86:89], v[22:25]
	v_mfma_f32_16x16x32_bf16 v[26:29], v[242:245], v[86:89], v[26:29]
	v_mfma_f32_16x16x32_bf16 v[30:33], v[246:249], v[86:89], v[30:33]
	v_mfma_f32_16x16x32_bf16 v[34:37], v[234:237], v[90:93], v[34:37]
	v_mfma_f32_16x16x32_bf16 v[38:41], v[238:241], v[90:93], v[38:41]
	v_mfma_f32_16x16x32_bf16 v[42:45], v[242:245], v[90:93], v[42:45]
	v_mfma_f32_16x16x32_bf16 v[46:49], v[246:249], v[90:93], v[46:49]
	v_mfma_f32_16x16x32_bf16 v[50:53], v[234:237], v[94:97], v[50:53]
	v_mfma_f32_16x16x32_bf16 v[54:57], v[238:241], v[94:97], v[54:57]
	v_mfma_f32_16x16x32_bf16 v[58:61], v[242:245], v[94:97], v[58:61]
	v_mfma_f32_16x16x32_bf16 v[62:65], v[246:249], v[94:97], v[62:65]
	ds_read_b128 v[234:237], v214 offset:12288
	ds_read_b128 v[238:241], v214 offset:13312
	ds_read_b128 v[242:245], v214 offset:14336
	ds_read_b128 v[246:249], v214 offset:15360
	s_waitcnt lgkmcnt(4)
	v_mfma_f32_16x16x32_bf16 v[2:5], v[218:221], v[98:101], v[2:5]
	v_mfma_f32_16x16x32_bf16 v[6:9], v[222:225], v[98:101], v[6:9]
	v_mfma_f32_16x16x32_bf16 v[10:13], v[226:229], v[98:101], v[10:13]
	v_mfma_f32_16x16x32_bf16 v[14:17], v[230:233], v[98:101], v[14:17]
	v_mfma_f32_16x16x32_bf16 v[18:21], v[218:221], v[102:105], v[18:21]
	v_mfma_f32_16x16x32_bf16 v[22:25], v[222:225], v[102:105], v[22:25]
	v_mfma_f32_16x16x32_bf16 v[26:29], v[226:229], v[102:105], v[26:29]
	v_mfma_f32_16x16x32_bf16 v[30:33], v[230:233], v[102:105], v[30:33]
	v_mfma_f32_16x16x32_bf16 v[34:37], v[218:221], v[106:109], v[34:37]
	v_mfma_f32_16x16x32_bf16 v[38:41], v[222:225], v[106:109], v[38:41]
	v_mfma_f32_16x16x32_bf16 v[42:45], v[226:229], v[106:109], v[42:45]
	v_mfma_f32_16x16x32_bf16 v[46:49], v[230:233], v[106:109], v[46:49]
	v_mfma_f32_16x16x32_bf16 v[50:53], v[218:221], v[110:113], v[50:53]
	v_mfma_f32_16x16x32_bf16 v[54:57], v[222:225], v[110:113], v[54:57]
	v_mfma_f32_16x16x32_bf16 v[58:61], v[226:229], v[110:113], v[58:61]
	v_mfma_f32_16x16x32_bf16 v[62:65], v[230:233], v[110:113], v[62:65]
	ds_read_b128 v[218:221], v214 offset:16384
	ds_read_b128 v[222:225], v214 offset:17408
	ds_read_b128 v[226:229], v214 offset:18432
	ds_read_b128 v[230:233], v214 offset:19456
	s_waitcnt lgkmcnt(4)
	v_mfma_f32_16x16x32_bf16 v[2:5], v[234:237], v[114:117], v[2:5]
	v_mfma_f32_16x16x32_bf16 v[6:9], v[238:241], v[114:117], v[6:9]
	v_mfma_f32_16x16x32_bf16 v[10:13], v[242:245], v[114:117], v[10:13]
	v_mfma_f32_16x16x32_bf16 v[14:17], v[246:249], v[114:117], v[14:17]
	v_mfma_f32_16x16x32_bf16 v[18:21], v[234:237], v[118:121], v[18:21]
	v_mfma_f32_16x16x32_bf16 v[22:25], v[238:241], v[118:121], v[22:25]
	v_mfma_f32_16x16x32_bf16 v[26:29], v[242:245], v[118:121], v[26:29]
	v_mfma_f32_16x16x32_bf16 v[30:33], v[246:249], v[118:121], v[30:33]
	v_mfma_f32_16x16x32_bf16 v[34:37], v[234:237], v[122:125], v[34:37]
	v_mfma_f32_16x16x32_bf16 v[38:41], v[238:241], v[122:125], v[38:41]
	v_mfma_f32_16x16x32_bf16 v[42:45], v[242:245], v[122:125], v[42:45]
	v_mfma_f32_16x16x32_bf16 v[46:49], v[246:249], v[122:125], v[46:49]
	v_mfma_f32_16x16x32_bf16 v[50:53], v[234:237], v[126:129], v[50:53]
	v_mfma_f32_16x16x32_bf16 v[54:57], v[238:241], v[126:129], v[54:57]
	v_mfma_f32_16x16x32_bf16 v[58:61], v[242:245], v[126:129], v[58:61]
	v_mfma_f32_16x16x32_bf16 v[62:65], v[246:249], v[126:129], v[62:65]
	s_waitcnt vmcnt(0)
	ds_read_b128 v[234:237], v214 offset:20480
	ds_read_b128 v[238:241], v214 offset:21504
	ds_read_b128 v[242:245], v214 offset:22528
	ds_read_b128 v[246:249], v214 offset:23552
	s_waitcnt lgkmcnt(4)
	v_mfma_f32_16x16x32_bf16 v[2:5], v[218:221], v[130:133], v[2:5]
	v_mfma_f32_16x16x32_bf16 v[6:9], v[222:225], v[130:133], v[6:9]
	v_mfma_f32_16x16x32_bf16 v[10:13], v[226:229], v[130:133], v[10:13]
	v_mfma_f32_16x16x32_bf16 v[14:17], v[230:233], v[130:133], v[14:17]
	v_mfma_f32_16x16x32_bf16 v[18:21], v[218:221], v[134:137], v[18:21]
	v_mfma_f32_16x16x32_bf16 v[22:25], v[222:225], v[134:137], v[22:25]
	v_mfma_f32_16x16x32_bf16 v[26:29], v[226:229], v[134:137], v[26:29]
	v_mfma_f32_16x16x32_bf16 v[30:33], v[230:233], v[134:137], v[30:33]
	v_mfma_f32_16x16x32_bf16 v[34:37], v[218:221], v[138:141], v[34:37]
	v_mfma_f32_16x16x32_bf16 v[38:41], v[222:225], v[138:141], v[38:41]
	v_mfma_f32_16x16x32_bf16 v[42:45], v[226:229], v[138:141], v[42:45]
	v_mfma_f32_16x16x32_bf16 v[46:49], v[230:233], v[138:141], v[46:49]
	v_mfma_f32_16x16x32_bf16 v[50:53], v[218:221], v[142:145], v[50:53]
	v_mfma_f32_16x16x32_bf16 v[54:57], v[222:225], v[142:145], v[54:57]
	v_mfma_f32_16x16x32_bf16 v[58:61], v[226:229], v[142:145], v[58:61]
	v_mfma_f32_16x16x32_bf16 v[62:65], v[230:233], v[142:145], v[62:65]
	ds_read_b128 v[218:221], v214 offset:24576
	ds_read_b128 v[222:225], v214 offset:25600
	ds_read_b128 v[226:229], v214 offset:26624
	ds_read_b128 v[230:233], v214 offset:27648
	s_waitcnt lgkmcnt(4)
	v_mfma_f32_16x16x32_bf16 v[2:5], v[234:237], v[146:149], v[2:5]
	v_mfma_f32_16x16x32_bf16 v[6:9], v[238:241], v[146:149], v[6:9]
	v_mfma_f32_16x16x32_bf16 v[10:13], v[242:245], v[146:149], v[10:13]
	v_mfma_f32_16x16x32_bf16 v[14:17], v[246:249], v[146:149], v[14:17]
	v_mfma_f32_16x16x32_bf16 v[18:21], v[234:237], v[150:153], v[18:21]
	v_mfma_f32_16x16x32_bf16 v[22:25], v[238:241], v[150:153], v[22:25]
	v_mfma_f32_16x16x32_bf16 v[26:29], v[242:245], v[150:153], v[26:29]
	v_mfma_f32_16x16x32_bf16 v[30:33], v[246:249], v[150:153], v[30:33]
	v_mfma_f32_16x16x32_bf16 v[34:37], v[234:237], v[154:157], v[34:37]
	v_mfma_f32_16x16x32_bf16 v[38:41], v[238:241], v[154:157], v[38:41]
	v_mfma_f32_16x16x32_bf16 v[42:45], v[242:245], v[154:157], v[42:45]
	v_mfma_f32_16x16x32_bf16 v[46:49], v[246:249], v[154:157], v[46:49]
	v_mfma_f32_16x16x32_bf16 v[50:53], v[234:237], v[158:161], v[50:53]
	v_mfma_f32_16x16x32_bf16 v[54:57], v[238:241], v[158:161], v[54:57]
	v_mfma_f32_16x16x32_bf16 v[58:61], v[242:245], v[158:161], v[58:61]
	v_mfma_f32_16x16x32_bf16 v[62:65], v[246:249], v[158:161], v[62:65]
	ds_read_b128 v[234:237], v214 offset:28672
	ds_read_b128 v[238:241], v214 offset:29696
	ds_read_b128 v[242:245], v214 offset:30720
	ds_read_b128 v[246:249], v214 offset:31744
	s_waitcnt lgkmcnt(4)
	v_mfma_f32_16x16x32_bf16 v[2:5], v[218:221], v[162:165], v[2:5]
	v_mfma_f32_16x16x32_bf16 v[6:9], v[222:225], v[162:165], v[6:9]
	v_mfma_f32_16x16x32_bf16 v[10:13], v[226:229], v[162:165], v[10:13]
	v_mfma_f32_16x16x32_bf16 v[14:17], v[230:233], v[162:165], v[14:17]
	v_mfma_f32_16x16x32_bf16 v[18:21], v[218:221], v[166:169], v[18:21]
	v_mfma_f32_16x16x32_bf16 v[22:25], v[222:225], v[166:169], v[22:25]
	v_mfma_f32_16x16x32_bf16 v[26:29], v[226:229], v[166:169], v[26:29]
	v_mfma_f32_16x16x32_bf16 v[30:33], v[230:233], v[166:169], v[30:33]
	v_mfma_f32_16x16x32_bf16 v[34:37], v[218:221], v[170:173], v[34:37]
	v_mfma_f32_16x16x32_bf16 v[38:41], v[222:225], v[170:173], v[38:41]
	v_mfma_f32_16x16x32_bf16 v[42:45], v[226:229], v[170:173], v[42:45]
	v_mfma_f32_16x16x32_bf16 v[46:49], v[230:233], v[170:173], v[46:49]
	v_mfma_f32_16x16x32_bf16 v[50:53], v[218:221], v[174:177], v[50:53]
	v_mfma_f32_16x16x32_bf16 v[54:57], v[222:225], v[174:177], v[54:57]
	v_mfma_f32_16x16x32_bf16 v[58:61], v[226:229], v[174:177], v[58:61]
	v_mfma_f32_16x16x32_bf16 v[62:65], v[230:233], v[174:177], v[62:65]
	s_waitcnt lgkmcnt(0)
	v_mfma_f32_16x16x32_bf16 v[2:5], v[234:237], v[178:181], v[2:5]
	v_mfma_f32_16x16x32_bf16 v[6:9], v[238:241], v[178:181], v[6:9]
	v_mfma_f32_16x16x32_bf16 v[10:13], v[242:245], v[178:181], v[10:13]
	v_mfma_f32_16x16x32_bf16 v[14:17], v[246:249], v[178:181], v[14:17]
	v_mfma_f32_16x16x32_bf16 v[18:21], v[234:237], v[182:185], v[18:21]
	v_mfma_f32_16x16x32_bf16 v[22:25], v[238:241], v[182:185], v[22:25]
	v_mfma_f32_16x16x32_bf16 v[26:29], v[242:245], v[182:185], v[26:29]
	v_mfma_f32_16x16x32_bf16 v[30:33], v[246:249], v[182:185], v[30:33]
	v_mfma_f32_16x16x32_bf16 v[34:37], v[234:237], v[186:189], v[34:37]
	v_mfma_f32_16x16x32_bf16 v[38:41], v[238:241], v[186:189], v[38:41]
	v_mfma_f32_16x16x32_bf16 v[42:45], v[242:245], v[186:189], v[42:45]
	v_mfma_f32_16x16x32_bf16 v[46:49], v[246:249], v[186:189], v[46:49]
	v_mfma_f32_16x16x32_bf16 v[50:53], v[234:237], v[190:193], v[50:53]
	v_mfma_f32_16x16x32_bf16 v[54:57], v[238:241], v[190:193], v[54:57]
	v_mfma_f32_16x16x32_bf16 v[58:61], v[242:245], v[190:193], v[58:61]
	v_mfma_f32_16x16x32_bf16 v[62:65], v[246:249], v[190:193], v[62:65]
	s_nop 7
	s_barrier
	ds_write_b128 v206, v[2:5] offset:0
	ds_write_b128 v206, v[6:9] offset:1024
	ds_write_b128 v206, v[10:13] offset:2048
	ds_write_b128 v206, v[14:17] offset:3072
	ds_write_b128 v206, v[18:21] offset:4096
	ds_write_b128 v206, v[22:25] offset:5120
	ds_write_b128 v206, v[26:29] offset:6144
	ds_write_b128 v206, v[30:33] offset:7168
	ds_write_b128 v206, v[34:37] offset:8192
	ds_write_b128 v206, v[38:41] offset:9216
	ds_write_b128 v206, v[42:45] offset:10240
	ds_write_b128 v206, v[46:49] offset:11264
	ds_write_b128 v206, v[50:53] offset:12288
	ds_write_b128 v206, v[54:57] offset:13312
	ds_write_b128 v206, v[58:61] offset:14336
	ds_write_b128 v206, v[62:65] offset:15360
	s_waitcnt lgkmcnt(0)
	s_barrier
	ds_read_b128 v[2:5], v207 offset:0
	ds_read_b128 v[6:9], v207 offset:16384
	ds_read_b128 v[10:13], v207 offset:32768
	ds_read_b128 v[14:17], v207 offset:49152
	ds_read_b128 v[18:21], v207 offset:1024
	ds_read_b128 v[22:25], v207 offset:17408
	ds_read_b128 v[26:29], v207 offset:33792
	ds_read_b128 v[30:33], v207 offset:50176
	ds_read_b128 v[34:37], v207 offset:2048
	ds_read_b128 v[38:41], v207 offset:18432
	ds_read_b128 v[42:45], v207 offset:34816
	ds_read_b128 v[46:49], v207 offset:51200
	ds_read_b128 v[50:53], v207 offset:3072
	ds_read_b128 v[54:57], v207 offset:19456
	ds_read_b128 v[58:61], v207 offset:35840
	ds_read_b128 v[62:65], v207 offset:52224
	s_waitcnt lgkmcnt(12)
	v_add_f32_e32 v2, v2, v6
	v_add_f32_e32 v3, v3, v7
	v_add_f32_e32 v4, v4, v8
	v_add_f32_e32 v5, v5, v9
	v_add_f32_e32 v10, v10, v14
	v_add_f32_e32 v11, v11, v15
	v_add_f32_e32 v12, v12, v16
	v_add_f32_e32 v13, v13, v17
	v_add_f32_e32 v2, v2, v10
	v_add_f32_e32 v3, v3, v11
	v_add_f32_e32 v4, v4, v12
	v_add_f32_e32 v5, v5, v13
	s_waitcnt lgkmcnt(8)
	v_add_f32_e32 v18, v18, v22
	v_add_f32_e32 v19, v19, v23
	v_add_f32_e32 v20, v20, v24
	v_add_f32_e32 v21, v21, v25
	v_add_f32_e32 v26, v26, v30
	v_add_f32_e32 v27, v27, v31
	v_add_f32_e32 v28, v28, v32
	v_add_f32_e32 v29, v29, v33
	v_add_f32_e32 v18, v18, v26
	v_add_f32_e32 v19, v19, v27
	v_add_f32_e32 v20, v20, v28
	v_add_f32_e32 v21, v21, v29
	s_waitcnt lgkmcnt(4)
	v_add_f32_e32 v34, v34, v38
	v_add_f32_e32 v35, v35, v39
	v_add_f32_e32 v36, v36, v40
	v_add_f32_e32 v37, v37, v41
	v_add_f32_e32 v42, v42, v46
	v_add_f32_e32 v43, v43, v47
	v_add_f32_e32 v44, v44, v48
	v_add_f32_e32 v45, v45, v49
	v_add_f32_e32 v34, v34, v42
	v_add_f32_e32 v35, v35, v43
	v_add_f32_e32 v36, v36, v44
	v_add_f32_e32 v37, v37, v45
	s_waitcnt lgkmcnt(0)
	v_add_f32_e32 v50, v50, v54
	v_add_f32_e32 v51, v51, v55
	v_add_f32_e32 v52, v52, v56
	v_add_f32_e32 v53, v53, v57
	v_add_f32_e32 v58, v58, v62
	v_add_f32_e32 v59, v59, v63
	v_add_f32_e32 v60, v60, v64
	v_add_f32_e32 v61, v61, v65
	v_add_f32_e32 v50, v50, v58
	v_add_f32_e32 v51, v51, v59
	v_add_f32_e32 v52, v52, v60
	v_add_f32_e32 v53, v53, v61
	s_cmp_eq_u32 s42, 0
	s_cbranch_scc1 .Linp1_nof32
	global_store_dwordx4 v210, v[2:5], s[38:39] offset:0
	global_store_dwordx4 v210, v[18:21], s[38:39] offset:64
	global_store_dwordx4 v210, v[34:37], s[38:39] offset:128
	global_store_dwordx4 v210, v[50:53], s[38:39] offset:192
	s_nop 1

.Lsmp5_unit:
	s_add_u32 s20, s16, 0x5100000
	s_addc_u32 s21, s17, 0
	s_add_u32 s22, s16, 0x900000
	s_addc_u32 s23, s17, 0
	s_add_u32 s24, s16, 0xf400000
	s_addc_u32 s25, s17, 0
	s_and_b32 s28, s12, 7
	s_lshr_b32 s29, s12, 3
	s_lshl_b32 s29, s29, 1
	s_add_u32 s29, s29, s6
	s_lshr_b32 s30, s29, 3
	s_lshl_b32 s28, s28, 3
	s_add_u32 s30, s30, s28
	s_and_b32 s31, s29, 7
	s_lshl_b32 s33, s31, 17
	s_lshl_b32 s34, s30, 17
	v_lshlrev_b32_e32 v215, 11, v202
	v_lshl_add_u32 v215, v203, 4, v215
	v_add_u32_e32 v194, s33, v204
	v_add_u32_e32 v198, s34, v215
	v_add_u32_e32 v195, s33, v204
	v_add_u32_e32 v199, s34, v215
	v_add_u32_e32 v196, s33, v204
	v_add_u32_e32 v200, s34, v215
	v_add_u32_e32 v197, s33, v204
	v_add_u32_e32 v201, s34, v215
	v_add_u32_e32 v195, 0x8000, v195
	v_add_u32_e32 v199, 0x8000, v199
	v_add_u32_e32 v196, 0x10000, v196
	v_add_u32_e32 v200, 0x10000, v200
	v_add_u32_e32 v197, 0x18000, v197
	v_add_u32_e32 v201, 0x18000, v201
	s_lshl_b32 s33, s31, 19
	s_lshl_b32 s34, s30, 7
	s_add_u32 s33, s33, s34
	v_add_u32_e32 v209, s33, v208
	s_lshl_b32 s44, s4, 8
	s_add_u32 s44, s22, s44
	s_addc_u32 s45, s23, 0
	s_lshl_b32 s46, s4, 14
	s_add_i32 m0, s46, 0x0
	s_nop 0
	global_load_lds_dwordx4 v198, s[44:45]
	s_add_i32 m0, s46, 0x400
	s_nop 0
	global_load_lds_dwordx4 v199, s[44:45]
	s_add_i32 m0, s46, 0x800
	s_nop 0
	global_load_lds_dwordx4 v200, s[44:45]
	s_add_i32 m0, s46, 0xc00
	s_nop 0
	global_load_lds_dwordx4 v201, s[44:45]
	s_add_u32 s44, s44, 64
	s_addc_u32 s45, s45, 0
	s_add_i32 m0, s46, 0x1000
	s_nop 0
	global_load_lds_dwordx4 v198, s[44:45]
	s_add_i32 m0, s46, 0x1400
	s_nop 0
	global_load_lds_dwordx4 v199, s[44:45]
	s_add_i32 m0, s46, 0x1800
	s_nop 0
	global_load_lds_dwordx4 v200, s[44:45]
	s_add_i32 m0, s46, 0x1c00
	s_nop 0
	global_load_lds_dwordx4 v201, s[44:45]
	s_add_u32 s44, s44, 64
	s_addc_u32 s45, s45, 0
	s_add_i32 m0, s46, 0x2000
	s_nop 0
	global_load_lds_dwordx4 v198, s[44:45]
	s_add_i32 m0, s46, 0x2400
	s_nop 0
	global_load_lds_dwordx4 v199, s[44:45]
	s_add_i32 m0, s46, 0x2800
	s_nop 0
	global_load_lds_dwordx4 v200, s[44:45]
	s_add_i32 m0, s46, 0x2c00
	s_nop 0
	global_load_lds_dwordx4 v201, s[44:45]
	s_add_u32 s44, s44, 64
	s_addc_u32 s45, s45, 0
	s_add_i32 m0, s46, 0x3000
	s_nop 0
	global_load_lds_dwordx4 v198, s[44:45]
	s_add_i32 m0, s46, 0x3400
	s_nop 0
	global_load_lds_dwordx4 v199, s[44:45]
	s_add_i32 m0, s46, 0x3800
	s_nop 0
	global_load_lds_dwordx4 v200, s[44:45]
	s_add_i32 m0, s46, 0x3c00
	s_nop 0
	global_load_lds_dwordx4 v201, s[44:45]
	global_load_dwordx4 v[66:69], v194, s[20:21] offset:0
	global_load_dwordx4 v[70:73], v195, s[20:21] offset:0
	global_load_dwordx4 v[74:77], v196, s[20:21] offset:0
	global_load_dwordx4 v[78:81], v197, s[20:21] offset:0
	global_load_dwordx4 v[82:85], v194, s[20:21] offset:64
	global_load_dwordx4 v[86:89], v195, s[20:21] offset:64
	global_load_dwordx4 v[90:93], v196, s[20:21] offset:64
	global_load_dwordx4 v[94:97], v197, s[20:21] offset:64
	global_load_dwordx4 v[98:101], v194, s[20:21] offset:128
	global_load_dwordx4 v[102:105], v195, s[20:21] offset:128
	global_load_dwordx4 v[106:109], v196, s[20:21] offset:128
	global_load_dwordx4 v[110:113], v197, s[20:21] offset:128
	global_load_dwordx4 v[114:117], v194, s[20:21] offset:192
	global_load_dwordx4 v[118:121], v195, s[20:21] offset:192
	global_load_dwordx4 v[122:125], v196, s[20:21] offset:192
	global_load_dwordx4 v[126:129], v197, s[20:21] offset:192
	global_load_dwordx4 v[130:133], v194, s[20:21] offset:256
	global_load_dwordx4 v[134:137], v195, s[20:21] offset:256
	global_load_dwordx4 v[138:141], v196, s[20:21] offset:256
	global_load_dwordx4 v[142:145], v197, s[20:21] offset:256
	global_load_dwordx4 v[146:149], v194, s[20:21] offset:320
	global_load_dwordx4 v[150:153], v195, s[20:21] offset:320
	global_load_dwordx4 v[154:157], v196, s[20:21] offset:320
	global_load_dwordx4 v[158:161], v197, s[20:21] offset:320
	global_load_dwordx4 v[162:165], v194, s[20:21] offset:384
	global_load_dwordx4 v[166:169], v195, s[20:21] offset:384
	global_load_dwordx4 v[170:173], v196, s[20:21] offset:384
	global_load_dwordx4 v[174:177], v197, s[20:21] offset:384
	global_load_dwordx4 v[178:181], v194, s[20:21] offset:448
	global_load_dwordx4 v[182:185], v195, s[20:21] offset:448
	global_load_dwordx4 v[186:189], v196, s[20:21] offset:448
	global_load_dwordx4 v[190:193], v197, s[20:21] offset:448
	s_waitcnt vmcnt(16)
	s_barrier
	s_lshl_b32 s47, s5, 15
	v_lshl_add_u32 v214, v205, 4, s47
	ds_read_b128 v[218:221], v214 offset:0
	ds_read_b128 v[222:225], v214 offset:1024
	ds_read_b128 v[226:229], v214 offset:2048
	ds_read_b128 v[230:233], v214 offset:3072
	ds_read_b128 v[234:237], v214 offset:4096
	ds_read_b128 v[238:241], v214 offset:5120
	ds_read_b128 v[242:245], v214 offset:6144
	ds_read_b128 v[246:249], v214 offset:7168
	s_waitcnt lgkmcnt(4)
	v_mfma_f32_16x16x32_bf16 v[2:5], v[218:221], v[66:69], 0
	v_mfma_f32_16x16x32_bf16 v[6:9], v[222:225], v[66:69], 0
	v_mfma_f32_16x16x32_bf16 v[10:13], v[226:229], v[66:69], 0
	v_mfma_f32_16x16x32_bf16 v[14:17], v[230:233], v[66:69], 0
	v_mfma_f32_16x16x32_bf16 v[18:21], v[218:221], v[70:73], 0
	v_mfma_f32_16x16x32_bf16 v[22:25], v[222:225], v[70:73], 0
	v_mfma_f32_16x16x32_bf16 v[26:29], v[226:229], v[70:73], 0
	v_mfma_f32_16x16x32_bf16 v[30:33], v[230:233], v[70:73], 0
	v_mfma_f32_16x16x32_bf16 v[34:37], v[218:221], v[74:77], 0
	v_mfma_f32_16x16x32_bf16 v[38:41], v[222:225], v[74:77], 0
	v_mfma_f32_16x16x32_bf16 v[42:45], v[226:229], v[74:77], 0
	v_mfma_f32_16x16x32_bf16 v[46:49], v[230:233], v[74:77], 0
	v_mfma_f32_16x16x32_bf16 v[50:53], v[218:221], v[78:81], 0
	v_mfma_f32_16x16x32_bf16 v[54:57], v[222:225], v[78:81], 0
	v_mfma_f32_16x16x32_bf16 v[58:61], v[226:229], v[78:81], 0
	v_mfma_f32_16x16x32_bf16 v[62:65], v[230:233], v[78:81], 0
	ds_read_b128 v[218:221], v214 offset:8192
	ds_read_b128 v[222:225], v214 offset:9216
	ds_read_b128 v[226:229], v214 offset:10240
	ds_read_b128 v[230:233], v214 offset:11264
	s_waitcnt lgkmcnt(4)
	v_mfma_f32_16x16x32_bf16 v[2:5], v[234:237], v[82:85], v[2:5]
	v_mfma_f32_16x16x32_bf16 v[6:9], v[238:241], v[82:85], v[6:9]
	v_mfma_f32_16x16x32_bf16 v[10:13], v[242:245], v[82:85], v[10:13]
	v_mfma_f32_16x16x32_bf16 v[14:17], v[246:249], v[82:85], v[14:17]
	v_mfma_f32_16x16x32_bf16 v[18:21], v[234:237], v[86:89], v[18:21]
	v_mfma_f32_16x16x32_bf16 v[22:25], v[238:241], v[86:89], v[22:25]
	v_mfma_f32_16x16x32_bf16 v[26:29], v[242:245], v[86:89], v[26:29]
	v_mfma_f32_16x16x32_bf16 v[30:33], v[246:249], v[86:89], v[30:33]
	v_mfma_f32_16x16x32_bf16 v[34:37], v[234:237], v[90:93], v[34:37]
	v_mfma_f32_16x16x32_bf16 v[38:41], v[238:241], v[90:93], v[38:41]
	v_mfma_f32_16x16x32_bf16 v[42:45], v[242:245], v[90:93], v[42:45]
	v_mfma_f32_16x16x32_bf16 v[46:49], v[246:249], v[90:93], v[46:49]
	v_mfma_f32_16x16x32_bf16 v[50:53], v[234:237], v[94:97], v[50:53]
	v_mfma_f32_16x16x32_bf16 v[54:57], v[238:241], v[94:97], v[54:57]
	v_mfma_f32_16x16x32_bf16 v[58:61], v[242:245], v[94:97], v[58:61]
	v_mfma_f32_16x16x32_bf16 v[62:65], v[246:249], v[94:97], v[62:65]
	ds_read_b128 v[234:237], v214 offset:12288
	ds_read_b128 v[238:241], v214 offset:13312
	ds_read_b128 v[242:245], v214 offset:14336
	ds_read_b128 v[246:249], v214 offset:15360
	s_waitcnt lgkmcnt(4)
	v_mfma_f32_16x16x32_bf16 v[2:5], v[218:221], v[98:101], v[2:5]
	v_mfma_f32_16x16x32_bf16 v[6:9], v[222:225], v[98:101], v[6:9]
	v_mfma_f32_16x16x32_bf16 v[10:13], v[226:229], v[98:101], v[10:13]
	v_mfma_f32_16x16x32_bf16 v[14:17], v[230:233], v[98:101], v[14:17]
	v_mfma_f32_16x16x32_bf16 v[18:21], v[218:221], v[102:105], v[18:21]
	v_mfma_f32_16x16x32_bf16 v[22:25], v[222:225], v[102:105], v[22:25]
	v_mfma_f32_16x16x32_bf16 v[26:29], v[226:229], v[102:105], v[26:29]
	v_mfma_f32_16x16x32_bf16 v[30:33], v[230:233], v[102:105], v[30:33]
	v_mfma_f32_16x16x32_bf16 v[34:37], v[218:221], v[106:109], v[34:37]
	v_mfma_f32_16x16x32_bf16 v[38:41], v[222:225], v[106:109], v[38:41]
	v_mfma_f32_16x16x32_bf16 v[42:45], v[226:229], v[106:109], v[42:45]
	v_mfma_f32_16x16x32_bf16 v[46:49], v[230:233], v[106:109], v[46:49]
	v_mfma_f32_16x16x32_bf16 v[50:53], v[218:221], v[110:113], v[50:53]
	v_mfma_f32_16x16x32_bf16 v[54:57], v[222:225], v[110:113], v[54:57]
	v_mfma_f32_16x16x32_bf16 v[58:61], v[226:229], v[110:113], v[58:61]
	v_mfma_f32_16x16x32_bf16 v[62:65], v[230:233], v[110:113], v[62:65]
	ds_read_b128 v[218:221], v214 offset:16384
	ds_read_b128 v[222:225], v214 offset:17408
	ds_read_b128 v[226:229], v214 offset:18432
	ds_read_b128 v[230:233], v214 offset:19456
	s_waitcnt lgkmcnt(4)
	v_mfma_f32_16x16x32_bf16 v[2:5], v[234:237], v[114:117], v[2:5]
	v_mfma_f32_16x16x32_bf16 v[6:9], v[238:241], v[114:117], v[6:9]
	v_mfma_f32_16x16x32_bf16 v[10:13], v[242:245], v[114:117], v[10:13]
	v_mfma_f32_16x16x32_bf16 v[14:17], v[246:249], v[114:117], v[14:17]
	v_mfma_f32_16x16x32_bf16 v[18:21], v[234:237], v[118:121], v[18:21]
	v_mfma_f32_16x16x32_bf16 v[22:25], v[238:241], v[118:121], v[22:25]
	v_mfma_f32_16x16x32_bf16 v[26:29], v[242:245], v[118:121], v[26:29]
	v_mfma_f32_16x16x32_bf16 v[30:33], v[246:249], v[118:121], v[30:33]
	v_mfma_f32_16x16x32_bf16 v[34:37], v[234:237], v[122:125], v[34:37]
	v_mfma_f32_16x16x32_bf16 v[38:41], v[238:241], v[122:125], v[38:41]
	v_mfma_f32_16x16x32_bf16 v[42:45], v[242:245], v[122:125], v[42:45]
	v_mfma_f32_16x16x32_bf16 v[46:49], v[246:249], v[122:125], v[46:49]
	v_mfma_f32_16x16x32_bf16 v[50:53], v[234:237], v[126:129], v[50:53]
	v_mfma_f32_16x16x32_bf16 v[54:57], v[238:241], v[126:129], v[54:57]
	v_mfma_f32_16x16x32_bf16 v[58:61], v[242:245], v[126:129], v[58:61]
	v_mfma_f32_16x16x32_bf16 v[62:65], v[246:249], v[126:129], v[62:65]
	s_waitcnt vmcnt(0)
	ds_read_b128 v[234:237], v214 offset:20480
	ds_read_b128 v[238:241], v214 offset:21504
	ds_read_b128 v[242:245], v214 offset:22528
	ds_read_b128 v[246:249], v214 offset:23552
	s_waitcnt lgkmcnt(4)
	v_mfma_f32_16x16x32_bf16 v[2:5], v[218:221], v[130:133], v[2:5]
	v_mfma_f32_16x16x32_bf16 v[6:9], v[222:225], v[130:133], v[6:9]
	v_mfma_f32_16x16x32_bf16 v[10:13], v[226:229], v[130:133], v[10:13]
	v_mfma_f32_16x16x32_bf16 v[14:17], v[230:233], v[130:133], v[14:17]
	v_mfma_f32_16x16x32_bf16 v[18:21], v[218:221], v[134:137], v[18:21]
	v_mfma_f32_16x16x32_bf16 v[22:25], v[222:225], v[134:137], v[22:25]
	v_mfma_f32_16x16x32_bf16 v[26:29], v[226:229], v[134:137], v[26:29]
	v_mfma_f32_16x16x32_bf16 v[30:33], v[230:233], v[134:137], v[30:33]
	v_mfma_f32_16x16x32_bf16 v[34:37], v[218:221], v[138:141], v[34:37]
	v_mfma_f32_16x16x32_bf16 v[38:41], v[222:225], v[138:141], v[38:41]
	v_mfma_f32_16x16x32_bf16 v[42:45], v[226:229], v[138:141], v[42:45]
	v_mfma_f32_16x16x32_bf16 v[46:49], v[230:233], v[138:141], v[46:49]
	v_mfma_f32_16x16x32_bf16 v[50:53], v[218:221], v[142:145], v[50:53]
	v_mfma_f32_16x16x32_bf16 v[54:57], v[222:225], v[142:145], v[54:57]
	v_mfma_f32_16x16x32_bf16 v[58:61], v[226:229], v[142:145], v[58:61]
	v_mfma_f32_16x16x32_bf16 v[62:65], v[230:233], v[142:145], v[62:65]
	ds_read_b128 v[218:221], v214 offset:24576
	ds_read_b128 v[222:225], v214 offset:25600
	ds_read_b128 v[226:229], v214 offset:26624
	ds_read_b128 v[230:233], v214 offset:27648
	s_waitcnt lgkmcnt(4)
	v_mfma_f32_16x16x32_bf16 v[2:5], v[234:237], v[146:149], v[2:5]
	v_mfma_f32_16x16x32_bf16 v[6:9], v[238:241], v[146:149], v[6:9]
	v_mfma_f32_16x16x32_bf16 v[10:13], v[242:245], v[146:149], v[10:13]
	v_mfma_f32_16x16x32_bf16 v[14:17], v[246:249], v[146:149], v[14:17]
	v_mfma_f32_16x16x32_bf16 v[18:21], v[234:237], v[150:153], v[18:21]
	v_mfma_f32_16x16x32_bf16 v[22:25], v[238:241], v[150:153], v[22:25]
	v_mfma_f32_16x16x32_bf16 v[26:29], v[242:245], v[150:153], v[26:29]
	v_mfma_f32_16x16x32_bf16 v[30:33], v[246:249], v[150:153], v[30:33]
	v_mfma_f32_16x16x32_bf16 v[34:37], v[234:237], v[154:157], v[34:37]
	v_mfma_f32_16x16x32_bf16 v[38:41], v[238:241], v[154:157], v[38:41]
	v_mfma_f32_16x16x32_bf16 v[42:45], v[242:245], v[154:157], v[42:45]
	v_mfma_f32_16x16x32_bf16 v[46:49], v[246:249], v[154:157], v[46:49]
	v_mfma_f32_16x16x32_bf16 v[50:53], v[234:237], v[158:161], v[50:53]
	v_mfma_f32_16x16x32_bf16 v[54:57], v[238:241], v[158:161], v[54:57]
	v_mfma_f32_16x16x32_bf16 v[58:61], v[242:245], v[158:161], v[58:61]
	v_mfma_f32_16x16x32_bf16 v[62:65], v[246:249], v[158:161], v[62:65]
	ds_read_b128 v[234:237], v214 offset:28672
	ds_read_b128 v[238:241], v214 offset:29696
	ds_read_b128 v[242:245], v214 offset:30720
	ds_read_b128 v[246:249], v214 offset:31744
	s_waitcnt lgkmcnt(4)
	v_mfma_f32_16x16x32_bf16 v[2:5], v[218:221], v[162:165], v[2:5]
	v_mfma_f32_16x16x32_bf16 v[6:9], v[222:225], v[162:165], v[6:9]
	v_mfma_f32_16x16x32_bf16 v[10:13], v[226:229], v[162:165], v[10:13]
	v_mfma_f32_16x16x32_bf16 v[14:17], v[230:233], v[162:165], v[14:17]
	v_mfma_f32_16x16x32_bf16 v[18:21], v[218:221], v[166:169], v[18:21]
	v_mfma_f32_16x16x32_bf16 v[22:25], v[222:225], v[166:169], v[22:25]
	v_mfma_f32_16x16x32_bf16 v[26:29], v[226:229], v[166:169], v[26:29]
	v_mfma_f32_16x16x32_bf16 v[30:33], v[230:233], v[166:169], v[30:33]
	v_mfma_f32_16x16x32_bf16 v[34:37], v[218:221], v[170:173], v[34:37]
	v_mfma_f32_16x16x32_bf16 v[38:41], v[222:225], v[170:173], v[38:41]
	v_mfma_f32_16x16x32_bf16 v[42:45], v[226:229], v[170:173], v[42:45]
	v_mfma_f32_16x16x32_bf16 v[46:49], v[230:233], v[170:173], v[46:49]
	v_mfma_f32_16x16x32_bf16 v[50:53], v[218:221], v[174:177], v[50:53]
	v_mfma_f32_16x16x32_bf16 v[54:57], v[222:225], v[174:177], v[54:57]
	v_mfma_f32_16x16x32_bf16 v[58:61], v[226:229], v[174:177], v[58:61]
	v_mfma_f32_16x16x32_bf16 v[62:65], v[230:233], v[174:177], v[62:65]
	s_waitcnt lgkmcnt(0)
	v_mfma_f32_16x16x32_bf16 v[2:5], v[234:237], v[178:181], v[2:5]
	v_mfma_f32_16x16x32_bf16 v[6:9], v[238:241], v[178:181], v[6:9]
	v_mfma_f32_16x16x32_bf16 v[10:13], v[242:245], v[178:181], v[10:13]
	v_mfma_f32_16x16x32_bf16 v[14:17], v[246:249], v[178:181], v[14:17]
	v_mfma_f32_16x16x32_bf16 v[18:21], v[234:237], v[182:185], v[18:21]
	v_mfma_f32_16x16x32_bf16 v[22:25], v[238:241], v[182:185], v[22:25]
	v_mfma_f32_16x16x32_bf16 v[26:29], v[242:245], v[182:185], v[26:29]
	v_mfma_f32_16x16x32_bf16 v[30:33], v[246:249], v[182:185], v[30:33]
	v_mfma_f32_16x16x32_bf16 v[34:37], v[234:237], v[186:189], v[34:37]
	v_mfma_f32_16x16x32_bf16 v[38:41], v[238:241], v[186:189], v[38:41]
	v_mfma_f32_16x16x32_bf16 v[42:45], v[242:245], v[186:189], v[42:45]
	v_mfma_f32_16x16x32_bf16 v[46:49], v[246:249], v[186:189], v[46:49]
	v_mfma_f32_16x16x32_bf16 v[50:53], v[234:237], v[190:193], v[50:53]
	v_mfma_f32_16x16x32_bf16 v[54:57], v[238:241], v[190:193], v[54:57]
	v_mfma_f32_16x16x32_bf16 v[58:61], v[242:245], v[190:193], v[58:61]
	v_mfma_f32_16x16x32_bf16 v[62:65], v[246:249], v[190:193], v[62:65]
	s_nop 7
	s_barrier
	ds_write_b128 v206, v[2:5] offset:0
	ds_write_b128 v206, v[6:9] offset:1024
	ds_write_b128 v206, v[10:13] offset:2048
	ds_write_b128 v206, v[14:17] offset:3072
	ds_write_b128 v206, v[18:21] offset:4096
	ds_write_b128 v206, v[22:25] offset:5120
	ds_write_b128 v206, v[26:29] offset:6144
	ds_write_b128 v206, v[30:33] offset:7168
	ds_write_b128 v206, v[34:37] offset:8192
	ds_write_b128 v206, v[38:41] offset:9216
	ds_write_b128 v206, v[42:45] offset:10240
	ds_write_b128 v206, v[46:49] offset:11264
	ds_write_b128 v206, v[50:53] offset:12288
	ds_write_b128 v206, v[54:57] offset:13312
	ds_write_b128 v206, v[58:61] offset:14336
	ds_write_b128 v206, v[62:65] offset:15360
	s_waitcnt lgkmcnt(0)
	s_barrier
	ds_read_b128 v[2:5], v207 offset:0
	ds_read_b128 v[6:9], v207 offset:16384
	ds_read_b128 v[10:13], v207 offset:32768
	ds_read_b128 v[14:17], v207 offset:49152
	ds_read_b128 v[18:21], v207 offset:1024
	ds_read_b128 v[22:25], v207 offset:17408
	ds_read_b128 v[26:29], v207 offset:33792
	ds_read_b128 v[30:33], v207 offset:50176
	ds_read_b128 v[34:37], v207 offset:2048
	ds_read_b128 v[38:41], v207 offset:18432
	ds_read_b128 v[42:45], v207 offset:34816
	ds_read_b128 v[46:49], v207 offset:51200
	ds_read_b128 v[50:53], v207 offset:3072
	ds_read_b128 v[54:57], v207 offset:19456
	ds_read_b128 v[58:61], v207 offset:35840
	ds_read_b128 v[62:65], v207 offset:52224
	s_waitcnt lgkmcnt(12)
	v_add_f32_e32 v2, v2, v6
	v_add_f32_e32 v3, v3, v7
	v_add_f32_e32 v4, v4, v8
	v_add_f32_e32 v5, v5, v9
	v_add_f32_e32 v10, v10, v14
	v_add_f32_e32 v11, v11, v15
	v_add_f32_e32 v12, v12, v16
	v_add_f32_e32 v13, v13, v17
	v_add_f32_e32 v2, v2, v10
	v_add_f32_e32 v3, v3, v11
	v_add_f32_e32 v4, v4, v12
	v_add_f32_e32 v5, v5, v13
	s_waitcnt lgkmcnt(8)
	v_add_f32_e32 v18, v18, v22
	v_add_f32_e32 v19, v19, v23
	v_add_f32_e32 v20, v20, v24
	v_add_f32_e32 v21, v21, v25
	v_add_f32_e32 v26, v26, v30
	v_add_f32_e32 v27, v27, v31
	v_add_f32_e32 v28, v28, v32
	v_add_f32_e32 v29, v29, v33
	v_add_f32_e32 v18, v18, v26
	v_add_f32_e32 v19, v19, v27
	v_add_f32_e32 v20, v20, v28
	v_add_f32_e32 v21, v21, v29
	s_waitcnt lgkmcnt(4)
	v_add_f32_e32 v34, v34, v38
	v_add_f32_e32 v35, v35, v39
	v_add_f32_e32 v36, v36, v40
	v_add_f32_e32 v37, v37, v41
	v_add_f32_e32 v42, v42, v46
	v_add_f32_e32 v43, v43, v47
	v_add_f32_e32 v44, v44, v48
	v_add_f32_e32 v45, v45, v49
	v_add_f32_e32 v34, v34, v42
	v_add_f32_e32 v35, v35, v43
	v_add_f32_e32 v36, v36, v44
	v_add_f32_e32 v37, v37, v45
	s_waitcnt lgkmcnt(0)
	v_add_f32_e32 v50, v50, v54
	v_add_f32_e32 v51, v51, v55
	v_add_f32_e32 v52, v52, v56
	v_add_f32_e32 v53, v53, v57
	v_add_f32_e32 v58, v58, v62
	v_add_f32_e32 v59, v59, v63
	v_add_f32_e32 v60, v60, v64
	v_add_f32_e32 v61, v61, v65
	v_add_f32_e32 v50, v50, v58
	v_add_f32_e32 v51, v51, v59
	v_add_f32_e32 v52, v52, v60
	v_add_f32_e32 v53, v53, v61
	v_max_f32_e32 v2, 0, v2
	v_max_f32_e32 v3, 0, v3
	v_max_f32_e32 v4, 0, v4
	v_max_f32_e32 v5, 0, v5
	v_mul_f32_e32 v2, v2, v2
	v_mul_f32_e32 v3, v3, v3
	v_mul_f32_e32 v4, v4, v4
	v_mul_f32_e32 v5, v5, v5
	v_cvt_pk_bf16_f32 v210, v2, v3
	v_cvt_pk_bf16_f32 v211, v4, v5
	global_store_dwordx2 v209, v[210:211], s[24:25] offset:0
	v_max_f32_e32 v18, 0, v18
	v_max_f32_e32 v19, 0, v19
	v_max_f32_e32 v20, 0, v20
	v_max_f32_e32 v21, 0, v21
	v_mul_f32_e32 v18, v18, v18
	v_mul_f32_e32 v19, v19, v19
	v_mul_f32_e32 v20, v20, v20
	v_mul_f32_e32 v21, v21, v21
	v_cvt_pk_bf16_f32 v212, v18, v19
	v_cvt_pk_bf16_f32 v213, v20, v21
	global_store_dwordx2 v209, v[212:213], s[24:25] offset:32
	v_max_f32_e32 v34, 0, v34
	v_max_f32_e32 v35, 0, v35
	v_max_f32_e32 v36, 0, v36
	v_max_f32_e32 v37, 0, v37
	v_mul_f32_e32 v34, v34, v34
	v_mul_f32_e32 v35, v35, v35
	v_mul_f32_e32 v36, v36, v36
	v_mul_f32_e32 v37, v37, v37
	v_cvt_pk_bf16_f32 v214, v34, v35
	v_cvt_pk_bf16_f32 v215, v36, v37
	global_store_dwordx2 v209, v[214:215], s[24:25] offset:64
	v_max_f32_e32 v50, 0, v50
	v_max_f32_e32 v51, 0, v51
	v_max_f32_e32 v52, 0, v52
	v_max_f32_e32 v53, 0, v53
	v_mul_f32_e32 v50, v50, v50
	v_mul_f32_e32 v51, v51, v51
	v_mul_f32_e32 v52, v52, v52
	v_mul_f32_e32 v53, v53, v53
	v_cvt_pk_bf16_f32 v216, v50, v51
	v_cvt_pk_bf16_f32 v217, v52, v53
	global_store_dwordx2 v209, v[216:217], s[24:25] offset:96
	s_barrier
	s_add_i32 s12, s12, s3
	s_cmpk_lt_u32 s12, 0x100
	s_cbranch_scc1 .Lsmp5_unit

.Linp8_unit:
	s_lshr_b32 s29, s12, 3
	s_cmp_gt_u32 s29, 23
	s_cbranch_scc1 .Linp8_next
	s_add_u32 s20, s16, 0x5100000
	s_addc_u32 s21, s17, 0
	s_add_u32 s22, s16, 0x1900000
	s_addc_u32 s23, s17, 0
	s_add_u32 s24, s16, 0xd400000
	s_addc_u32 s25, s17, 0
	s_and_b32 s28, s12, 7
	s_lshl_b32 s29, s29, 1
	s_add_u32 s29, s29, s6
	s_lshr_b32 s30, s29, 3
	s_mul_i32 s28, s28, 6
	s_add_u32 s30, s30, s28
	s_and_b32 s31, s29, 7
	s_lshl_b32 s33, s31, 17
	s_lshl_b32 s34, s30, 17
	v_lshlrev_b32_e32 v215, 11, v202
	v_lshl_add_u32 v215, v203, 4, v215
	v_add_u32_e32 v194, s33, v204
	v_add_u32_e32 v198, s34, v215
	v_add_u32_e32 v195, s33, v204
	v_add_u32_e32 v199, s34, v215
	v_add_u32_e32 v196, s33, v204
	v_add_u32_e32 v200, s34, v215
	v_add_u32_e32 v197, s33, v204
	v_add_u32_e32 v201, s34, v215
	v_add_u32_e32 v195, 0x8000, v195
	v_add_u32_e32 v199, 0x8000, v199
	v_add_u32_e32 v196, 0x10000, v196
	v_add_u32_e32 v200, 0x10000, v200
	v_add_u32_e32 v197, 0x18000, v197
	v_add_u32_e32 v201, 0x18000, v201
	s_mul_i32 s33, s31, 0x60000
	s_lshl_b32 s34, s30, 7
	s_add_u32 s33, s33, s34
	v_add_u32_e32 v211, s33, v209
	s_lshr_b32 s35, s30, 4
	s_and_b32 s36, s30, 15
	s_lshl_b32 s36, s36, 8
	s_mov_b32 s37, 0x3f800000
	s_mov_b32 s42, 1
	s_cmp_eq_u32 s35, 0
	s_cselect_b32 s37, 0x3e38aa3b, s37
	s_cselect_b32 s42, 0, s42
	s_sub_u32 s43, s35, 1
	s_lshl_b32 s43, s43, 24
	s_lshl_b32 s44, s31, 21
	s_add_u32 s43, s43, s44
	s_add_u32 s43, s43, s36
	s_add_u32 s38, s40, s43
	s_addc_u32 s39, s41, 0
	s_add_u32 s38, s38, 0xd844000
	s_addc_u32 s39, s39, 0
	s_lshl_b32 s44, s4, 8
	s_add_u32 s44, s22, s44
	s_addc_u32 s45, s23, 0
	s_lshl_b32 s46, s4, 14
	s_add_i32 m0, s46, 0x0
	s_nop 0
	global_load_lds_dwordx4 v198, s[44:45]
	s_add_i32 m0, s46, 0x400
	s_nop 0
	global_load_lds_dwordx4 v199, s[44:45]
	s_add_i32 m0, s46, 0x800
	s_nop 0
	global_load_lds_dwordx4 v200, s[44:45]
	s_add_i32 m0, s46, 0xc00
	s_nop 0
	global_load_lds_dwordx4 v201, s[44:45]
	s_add_u32 s44, s44, 64
	s_addc_u32 s45, s45, 0
	s_add_i32 m0, s46, 0x1000
	s_nop 0
	global_load_lds_dwordx4 v198, s[44:45]
	s_add_i32 m0, s46, 0x1400
	s_nop 0
	global_load_lds_dwordx4 v199, s[44:45]
	s_add_i32 m0, s46, 0x1800
	s_nop 0
	global_load_lds_dwordx4 v200, s[44:45]
	s_add_i32 m0, s46, 0x1c00
	s_nop 0
	global_load_lds_dwordx4 v201, s[44:45]
	s_add_u32 s44, s44, 64
	s_addc_u32 s45, s45, 0
	s_add_i32 m0, s46, 0x2000
	s_nop 0
	global_load_lds_dwordx4 v198, s[44:45]
	s_add_i32 m0, s46, 0x2400
	s_nop 0
	global_load_lds_dwordx4 v199, s[44:45]
	s_add_i32 m0, s46, 0x2800
	s_nop 0
	global_load_lds_dwordx4 v200, s[44:45]
	s_add_i32 m0, s46, 0x2c00
	s_nop 0
	global_load_lds_dwordx4 v201, s[44:45]
	s_add_u32 s44, s44, 64
	s_addc_u32 s45, s45, 0
	s_add_i32 m0, s46, 0x3000
	s_nop 0
	global_load_lds_dwordx4 v198, s[44:45]
	s_add_i32 m0, s46, 0x3400
	s_nop 0
	global_load_lds_dwordx4 v199, s[44:45]
	s_add_i32 m0, s46, 0x3800
	s_nop 0
	global_load_lds_dwordx4 v200, s[44:45]
	s_add_i32 m0, s46, 0x3c00
	s_nop 0
	global_load_lds_dwordx4 v201, s[44:45]
	global_load_dwordx4 v[66:69], v194, s[20:21] offset:0
	global_load_dwordx4 v[70:73], v195, s[20:21] offset:0
	global_load_dwordx4 v[74:77], v196, s[20:21] offset:0
	global_load_dwordx4 v[78:81], v197, s[20:21] offset:0
	global_load_dwordx4 v[82:85], v194, s[20:21] offset:64
	global_load_dwordx4 v[86:89], v195, s[20:21] offset:64
	global_load_dwordx4 v[90:93], v196, s[20:21] offset:64
	global_load_dwordx4 v[94:97], v197, s[20:21] offset:64
	global_load_dwordx4 v[98:101], v194, s[20:21] offset:128
	global_load_dwordx4 v[102:105], v195, s[20:21] offset:128
	global_load_dwordx4 v[106:109], v196, s[20:21] offset:128
	global_load_dwordx4 v[110:113], v197, s[20:21] offset:128
	global_load_dwordx4 v[114:117], v194, s[20:21] offset:192
	global_load_dwordx4 v[118:121], v195, s[20:21] offset:192
	global_load_dwordx4 v[122:125], v196, s[20:21] offset:192
	global_load_dwordx4 v[126:129], v197, s[20:21] offset:192
	global_load_dwordx4 v[130:133], v194, s[20:21] offset:256
	global_load_dwordx4 v[134:137], v195, s[20:21] offset:256
	global_load_dwordx4 v[138:141], v196, s[20:21] offset:256
	global_load_dwordx4 v[142:145], v197, s[20:21] offset:256
	global_load_dwordx4 v[146:149], v194, s[20:21] offset:320
	global_load_dwordx4 v[150:153], v195, s[20:21] offset:320
	global_load_dwordx4 v[154:157], v196, s[20:21] offset:320
	global_load_dwordx4 v[158:161], v197, s[20:21] offset:320
	global_load_dwordx4 v[162:165], v194, s[20:21] offset:384
	global_load_dwordx4 v[166:169], v195, s[20:21] offset:384
	global_load_dwordx4 v[170:173], v196, s[20:21] offset:384
	global_load_dwordx4 v[174:177], v197, s[20:21] offset:384
	global_load_dwordx4 v[178:181], v194, s[20:21] offset:448
	global_load_dwordx4 v[182:185], v195, s[20:21] offset:448
	global_load_dwordx4 v[186:189], v196, s[20:21] offset:448
	global_load_dwordx4 v[190:193], v197, s[20:21] offset:448
	s_waitcnt vmcnt(16)
	s_barrier
	s_lshl_b32 s47, s5, 15
	v_lshl_add_u32 v214, v205, 4, s47
	ds_read_b128 v[218:221], v214 offset:0
	ds_read_b128 v[222:225], v214 offset:1024
	ds_read_b128 v[226:229], v214 offset:2048
	ds_read_b128 v[230:233], v214 offset:3072
	ds_read_b128 v[234:237], v214 offset:4096
	ds_read_b128 v[238:241], v214 offset:5120
	ds_read_b128 v[242:245], v214 offset:6144
	ds_read_b128 v[246:249], v214 offset:7168
	s_waitcnt lgkmcnt(4)
	v_mfma_f32_16x16x32_bf16 v[2:5], v[218:221], v[66:69], 0
	v_mfma_f32_16x16x32_bf16 v[6:9], v[222:225], v[66:69], 0
	v_mfma_f32_16x16x32_bf16 v[10:13], v[226:229], v[66:69], 0
	v_mfma_f32_16x16x32_bf16 v[14:17], v[230:233], v[66:69], 0
	v_mfma_f32_16x16x32_bf16 v[18:21], v[218:221], v[70:73], 0
	v_mfma_f32_16x16x32_bf16 v[22:25], v[222:225], v[70:73], 0
	v_mfma_f32_16x16x32_bf16 v[26:29], v[226:229], v[70:73], 0
	v_mfma_f32_16x16x32_bf16 v[30:33], v[230:233], v[70:73], 0
	v_mfma_f32_16x16x32_bf16 v[34:37], v[218:221], v[74:77], 0
	v_mfma_f32_16x16x32_bf16 v[38:41], v[222:225], v[74:77], 0
	v_mfma_f32_16x16x32_bf16 v[42:45], v[226:229], v[74:77], 0
	v_mfma_f32_16x16x32_bf16 v[46:49], v[230:233], v[74:77], 0
	v_mfma_f32_16x16x32_bf16 v[50:53], v[218:221], v[78:81], 0
	v_mfma_f32_16x16x32_bf16 v[54:57], v[222:225], v[78:81], 0
	v_mfma_f32_16x16x32_bf16 v[58:61], v[226:229], v[78:81], 0
	v_mfma_f32_16x16x32_bf16 v[62:65], v[230:233], v[78:81], 0
	ds_read_b128 v[218:221], v214 offset:8192
	ds_read_b128 v[222:225], v214 offset:9216
	ds_read_b128 v[226:229], v214 offset:10240
	ds_read_b128 v[230:233], v214 offset:11264
	s_waitcnt lgkmcnt(4)
	v_mfma_f32_16x16x32_bf16 v[2:5], v[234:237], v[82:85], v[2:5]
	v_mfma_f32_16x16x32_bf16 v[6:9], v[238:241], v[82:85], v[6:9]
	v_mfma_f32_16x16x32_bf16 v[10:13], v[242:245], v[82:85], v[10:13]
	v_mfma_f32_16x16x32_bf16 v[14:17], v[246:249], v[82:85], v[14:17]
	v_mfma_f32_16x16x32_bf16 v[18:21], v[234:237], v[86:89], v[18:21]
	v_mfma_f32_16x16x32_bf16 v[22:25], v[238:241], v[86:89], v[22:25]
	v_mfma_f32_16x16x32_bf16 v[26:29], v[242:245], v[86:89], v[26:29]
	v_mfma_f32_16x16x32_bf16 v[30:33], v[246:249], v[86:89], v[30:33]
	v_mfma_f32_16x16x32_bf16 v[34:37], v[234:237], v[90:93], v[34:37]
	v_mfma_f32_16x16x32_bf16 v[38:41], v[238:241], v[90:93], v[38:41]
	v_mfma_f32_16x16x32_bf16 v[42:45], v[242:245], v[90:93], v[42:45]
	v_mfma_f32_16x16x32_bf16 v[46:49], v[246:249], v[90:93], v[46:49]
	v_mfma_f32_16x16x32_bf16 v[50:53], v[234:237], v[94:97], v[50:53]
	v_mfma_f32_16x16x32_bf16 v[54:57], v[238:241], v[94:97], v[54:57]
	v_mfma_f32_16x16x32_bf16 v[58:61], v[242:245], v[94:97], v[58:61]
	v_mfma_f32_16x16x32_bf16 v[62:65], v[246:249], v[94:97], v[62:65]
	ds_read_b128 v[234:237], v214 offset:12288
	ds_read_b128 v[238:241], v214 offset:13312
	ds_read_b128 v[242:245], v214 offset:14336
	ds_read_b128 v[246:249], v214 offset:15360
	s_waitcnt lgkmcnt(4)
	v_mfma_f32_16x16x32_bf16 v[2:5], v[218:221], v[98:101], v[2:5]
	v_mfma_f32_16x16x32_bf16 v[6:9], v[222:225], v[98:101], v[6:9]
	v_mfma_f32_16x16x32_bf16 v[10:13], v[226:229], v[98:101], v[10:13]
	v_mfma_f32_16x16x32_bf16 v[14:17], v[230:233], v[98:101], v[14:17]
	v_mfma_f32_16x16x32_bf16 v[18:21], v[218:221], v[102:105], v[18:21]
	v_mfma_f32_16x16x32_bf16 v[22:25], v[222:225], v[102:105], v[22:25]
	v_mfma_f32_16x16x32_bf16 v[26:29], v[226:229], v[102:105], v[26:29]
	v_mfma_f32_16x16x32_bf16 v[30:33], v[230:233], v[102:105], v[30:33]
	v_mfma_f32_16x16x32_bf16 v[34:37], v[218:221], v[106:109], v[34:37]
	v_mfma_f32_16x16x32_bf16 v[38:41], v[222:225], v[106:109], v[38:41]
	v_mfma_f32_16x16x32_bf16 v[42:45], v[226:229], v[106:109], v[42:45]
	v_mfma_f32_16x16x32_bf16 v[46:49], v[230:233], v[106:109], v[46:49]
	v_mfma_f32_16x16x32_bf16 v[50:53], v[218:221], v[110:113], v[50:53]
	v_mfma_f32_16x16x32_bf16 v[54:57], v[222:225], v[110:113], v[54:57]
	v_mfma_f32_16x16x32_bf16 v[58:61], v[226:229], v[110:113], v[58:61]
	v_mfma_f32_16x16x32_bf16 v[62:65], v[230:233], v[110:113], v[62:65]
	ds_read_b128 v[218:221], v214 offset:16384
	ds_read_b128 v[222:225], v214 offset:17408
	ds_read_b128 v[226:229], v214 offset:18432
	ds_read_b128 v[230:233], v214 offset:19456
	s_waitcnt lgkmcnt(4)
	v_mfma_f32_16x16x32_bf16 v[2:5], v[234:237], v[114:117], v[2:5]
	v_mfma_f32_16x16x32_bf16 v[6:9], v[238:241], v[114:117], v[6:9]
	v_mfma_f32_16x16x32_bf16 v[10:13], v[242:245], v[114:117], v[10:13]
	v_mfma_f32_16x16x32_bf16 v[14:17], v[246:249], v[114:117], v[14:17]
	v_mfma_f32_16x16x32_bf16 v[18:21], v[234:237], v[118:121], v[18:21]
	v_mfma_f32_16x16x32_bf16 v[22:25], v[238:241], v[118:121], v[22:25]
	v_mfma_f32_16x16x32_bf16 v[26:29], v[242:245], v[118:121], v[26:29]
	v_mfma_f32_16x16x32_bf16 v[30:33], v[246:249], v[118:121], v[30:33]
	v_mfma_f32_16x16x32_bf16 v[34:37], v[234:237], v[122:125], v[34:37]
	v_mfma_f32_16x16x32_bf16 v[38:41], v[238:241], v[122:125], v[38:41]
	v_mfma_f32_16x16x32_bf16 v[42:45], v[242:245], v[122:125], v[42:45]
	v_mfma_f32_16x16x32_bf16 v[46:49], v[246:249], v[122:125], v[46:49]
	v_mfma_f32_16x16x32_bf16 v[50:53], v[234:237], v[126:129], v[50:53]
	v_mfma_f32_16x16x32_bf16 v[54:57], v[238:241], v[126:129], v[54:57]
	v_mfma_f32_16x16x32_bf16 v[58:61], v[242:245], v[126:129], v[58:61]
	v_mfma_f32_16x16x32_bf16 v[62:65], v[246:249], v[126:129], v[62:65]
	s_waitcnt vmcnt(0)
	ds_read_b128 v[234:237], v214 offset:20480
	ds_read_b128 v[238:241], v214 offset:21504
	ds_read_b128 v[242:245], v214 offset:22528
	ds_read_b128 v[246:249], v214 offset:23552
	s_waitcnt lgkmcnt(4)
	v_mfma_f32_16x16x32_bf16 v[2:5], v[218:221], v[130:133], v[2:5]
	v_mfma_f32_16x16x32_bf16 v[6:9], v[222:225], v[130:133], v[6:9]
	v_mfma_f32_16x16x32_bf16 v[10:13], v[226:229], v[130:133], v[10:13]
	v_mfma_f32_16x16x32_bf16 v[14:17], v[230:233], v[130:133], v[14:17]
	v_mfma_f32_16x16x32_bf16 v[18:21], v[218:221], v[134:137], v[18:21]
	v_mfma_f32_16x16x32_bf16 v[22:25], v[222:225], v[134:137], v[22:25]
	v_mfma_f32_16x16x32_bf16 v[26:29], v[226:229], v[134:137], v[26:29]
	v_mfma_f32_16x16x32_bf16 v[30:33], v[230:233], v[134:137], v[30:33]
	v_mfma_f32_16x16x32_bf16 v[34:37], v[218:221], v[138:141], v[34:37]
	v_mfma_f32_16x16x32_bf16 v[38:41], v[222:225], v[138:141], v[38:41]
	v_mfma_f32_16x16x32_bf16 v[42:45], v[226:229], v[138:141], v[42:45]
	v_mfma_f32_16x16x32_bf16 v[46:49], v[230:233], v[138:141], v[46:49]
	v_mfma_f32_16x16x32_bf16 v[50:53], v[218:221], v[142:145], v[50:53]
	v_mfma_f32_16x16x32_bf16 v[54:57], v[222:225], v[142:145], v[54:57]
	v_mfma_f32_16x16x32_bf16 v[58:61], v[226:229], v[142:145], v[58:61]
	v_mfma_f32_16x16x32_bf16 v[62:65], v[230:233], v[142:145], v[62:65]
	ds_read_b128 v[218:221], v214 offset:24576
	ds_read_b128 v[222:225], v214 offset:25600
	ds_read_b128 v[226:229], v214 offset:26624
	ds_read_b128 v[230:233], v214 offset:27648
	s_waitcnt lgkmcnt(4)
	v_mfma_f32_16x16x32_bf16 v[2:5], v[234:237], v[146:149], v[2:5]
	v_mfma_f32_16x16x32_bf16 v[6:9], v[238:241], v[146:149], v[6:9]
	v_mfma_f32_16x16x32_bf16 v[10:13], v[242:245], v[146:149], v[10:13]
	v_mfma_f32_16x16x32_bf16 v[14:17], v[246:249], v[146:149], v[14:17]
	v_mfma_f32_16x16x32_bf16 v[18:21], v[234:237], v[150:153], v[18:21]
	v_mfma_f32_16x16x32_bf16 v[22:25], v[238:241], v[150:153], v[22:25]
	v_mfma_f32_16x16x32_bf16 v[26:29], v[242:245], v[150:153], v[26:29]
	v_mfma_f32_16x16x32_bf16 v[30:33], v[246:249], v[150:153], v[30:33]
	v_mfma_f32_16x16x32_bf16 v[34:37], v[234:237], v[154:157], v[34:37]
	v_mfma_f32_16x16x32_bf16 v[38:41], v[238:241], v[154:157], v[38:41]
	v_mfma_f32_16x16x32_bf16 v[42:45], v[242:245], v[154:157], v[42:45]
	v_mfma_f32_16x16x32_bf16 v[46:49], v[246:249], v[154:157], v[46:49]
	v_mfma_f32_16x16x32_bf16 v[50:53], v[234:237], v[158:161], v[50:53]
	v_mfma_f32_16x16x32_bf16 v[54:57], v[238:241], v[158:161], v[54:57]
	v_mfma_f32_16x16x32_bf16 v[58:61], v[242:245], v[158:161], v[58:61]
	v_mfma_f32_16x16x32_bf16 v[62:65], v[246:249], v[158:161], v[62:65]
	ds_read_b128 v[234:237], v214 offset:28672
	ds_read_b128 v[238:241], v214 offset:29696
	ds_read_b128 v[242:245], v214 offset:30720
	ds_read_b128 v[246:249], v214 offset:31744
	s_waitcnt lgkmcnt(4)
	v_mfma_f32_16x16x32_bf16 v[2:5], v[218:221], v[162:165], v[2:5]
	v_mfma_f32_16x16x32_bf16 v[6:9], v[222:225], v[162:165], v[6:9]
	v_mfma_f32_16x16x32_bf16 v[10:13], v[226:229], v[162:165], v[10:13]
	v_mfma_f32_16x16x32_bf16 v[14:17], v[230:233], v[162:165], v[14:17]
	v_mfma_f32_16x16x32_bf16 v[18:21], v[218:221], v[166:169], v[18:21]
	v_mfma_f32_16x16x32_bf16 v[22:25], v[222:225], v[166:169], v[22:25]
	v_mfma_f32_16x16x32_bf16 v[26:29], v[226:229], v[166:169], v[26:29]
	v_mfma_f32_16x16x32_bf16 v[30:33], v[230:233], v[166:169], v[30:33]
	v_mfma_f32_16x16x32_bf16 v[34:37], v[218:221], v[170:173], v[34:37]
	v_mfma_f32_16x16x32_bf16 v[38:41], v[222:225], v[170:173], v[38:41]
	v_mfma_f32_16x16x32_bf16 v[42:45], v[226:229], v[170:173], v[42:45]
	v_mfma_f32_16x16x32_bf16 v[46:49], v[230:233], v[170:173], v[46:49]
	v_mfma_f32_16x16x32_bf16 v[50:53], v[218:221], v[174:177], v[50:53]
	v_mfma_f32_16x16x32_bf16 v[54:57], v[222:225], v[174:177], v[54:57]
	v_mfma_f32_16x16x32_bf16 v[58:61], v[226:229], v[174:177], v[58:61]
	v_mfma_f32_16x16x32_bf16 v[62:65], v[230:233], v[174:177], v[62:65]
	s_waitcnt lgkmcnt(0)
	v_mfma_f32_16x16x32_bf16 v[2:5], v[234:237], v[178:181], v[2:5]
	v_mfma_f32_16x16x32_bf16 v[6:9], v[238:241], v[178:181], v[6:9]
	v_mfma_f32_16x16x32_bf16 v[10:13], v[242:245], v[178:181], v[10:13]
	v_mfma_f32_16x16x32_bf16 v[14:17], v[246:249], v[178:181], v[14:17]
	v_mfma_f32_16x16x32_bf16 v[18:21], v[234:237], v[182:185], v[18:21]
	v_mfma_f32_16x16x32_bf16 v[22:25], v[238:241], v[182:185], v[22:25]
	v_mfma_f32_16x16x32_bf16 v[26:29], v[242:245], v[182:185], v[26:29]
	v_mfma_f32_16x16x32_bf16 v[30:33], v[246:249], v[182:185], v[30:33]
	v_mfma_f32_16x16x32_bf16 v[34:37], v[234:237], v[186:189], v[34:37]
	v_mfma_f32_16x16x32_bf16 v[38:41], v[238:241], v[186:189], v[38:41]
	v_mfma_f32_16x16x32_bf16 v[42:45], v[242:245], v[186:189], v[42:45]
	v_mfma_f32_16x16x32_bf16 v[46:49], v[246:249], v[186:189], v[46:49]
	v_mfma_f32_16x16x32_bf16 v[50:53], v[234:237], v[190:193], v[50:53]
	v_mfma_f32_16x16x32_bf16 v[54:57], v[238:241], v[190:193], v[54:57]
	v_mfma_f32_16x16x32_bf16 v[58:61], v[242:245], v[190:193], v[58:61]
	v_mfma_f32_16x16x32_bf16 v[62:65], v[246:249], v[190:193], v[62:65]
	s_nop 7
	s_barrier
	ds_write_b128 v206, v[2:5] offset:0
	ds_write_b128 v206, v[6:9] offset:1024
	ds_write_b128 v206, v[10:13] offset:2048
	ds_write_b128 v206, v[14:17] offset:3072
	ds_write_b128 v206, v[18:21] offset:4096
	ds_write_b128 v206, v[22:25] offset:5120
	ds_write_b128 v206, v[26:29] offset:6144
	ds_write_b128 v206, v[30:33] offset:7168
	ds_write_b128 v206, v[34:37] offset:8192
	ds_write_b128 v206, v[38:41] offset:9216
	ds_write_b128 v206, v[42:45] offset:10240
	ds_write_b128 v206, v[46:49] offset:11264
	ds_write_b128 v206, v[50:53] offset:12288
	ds_write_b128 v206, v[54:57] offset:13312
	ds_write_b128 v206, v[58:61] offset:14336
	ds_write_b128 v206, v[62:65] offset:15360
	s_waitcnt lgkmcnt(0)
	s_barrier
	ds_read_b128 v[2:5], v207 offset:0
	ds_read_b128 v[6:9], v207 offset:16384
	ds_read_b128 v[10:13], v207 offset:32768
	ds_read_b128 v[14:17], v207 offset:49152
	ds_read_b128 v[18:21], v207 offset:1024
	ds_read_b128 v[22:25], v207 offset:17408
	ds_read_b128 v[26:29], v207 offset:33792
	ds_read_b128 v[30:33], v207 offset:50176
	ds_read_b128 v[34:37], v207 offset:2048
	ds_read_b128 v[38:41], v207 offset:18432
	ds_read_b128 v[42:45], v207 offset:34816
	ds_read_b128 v[46:49], v207 offset:51200
	ds_read_b128 v[50:53], v207 offset:3072
	ds_read_b128 v[54:57], v207 offset:19456
	ds_read_b128 v[58:61], v207 offset:35840
	ds_read_b128 v[62:65], v207 offset:52224
	s_waitcnt lgkmcnt(12)
	v_add_f32_e32 v2, v2, v6
	v_add_f32_e32 v3, v3, v7
	v_add_f32_e32 v4, v4, v8
	v_add_f32_e32 v5, v5, v9
	v_add_f32_e32 v10, v10, v14
	v_add_f32_e32 v11, v11, v15
	v_add_f32_e32 v12, v12, v16
	v_add_f32_e32 v13, v13, v17
	v_add_f32_e32 v2, v2, v10
	v_add_f32_e32 v3, v3, v11
	v_add_f32_e32 v4, v4, v12
	v_add_f32_e32 v5, v5, v13
	s_waitcnt lgkmcnt(8)
	v_add_f32_e32 v18, v18, v22
	v_add_f32_e32 v19, v19, v23
	v_add_f32_e32 v20, v20, v24
	v_add_f32_e32 v21, v21, v25
	v_add_f32_e32 v26, v26, v30
	v_add_f32_e32 v27, v27, v31
	v_add_f32_e32 v28, v28, v32
	v_add_f32_e32 v29, v29, v33
	v_add_f32_e32 v18, v18, v26
	v_add_f32_e32 v19, v19, v27
	v_add_f32_e32 v20, v20, v28
	v_add_f32_e32 v21, v21, v29
	s_waitcnt lgkmcnt(4)
	v_add_f32_e32 v34, v34, v38
	v_add_f32_e32 v35, v35, v39
	v_add_f32_e32 v36, v36, v40
	v_add_f32_e32 v37, v37, v41
	v_add_f32_e32 v42, v42, v46
	v_add_f32_e32 v43, v43, v47
	v_add_f32_e32 v44, v44, v48
	v_add_f32_e32 v45, v45, v49
	v_add_f32_e32 v34, v34, v42
	v_add_f32_e32 v35, v35, v43
	v_add_f32_e32 v36, v36, v44
	v_add_f32_e32 v37, v37, v45
	s_waitcnt lgkmcnt(0)
	v_add_f32_e32 v50, v50, v54
	v_add_f32_e32 v51, v51, v55
	v_add_f32_e32 v52, v52, v56
	v_add_f32_e32 v53, v53, v57
	v_add_f32_e32 v58, v58, v62
	v_add_f32_e32 v59, v59, v63
	v_add_f32_e32 v60, v60, v64
	v_add_f32_e32 v61, v61, v65
	v_add_f32_e32 v50, v50, v58
	v_add_f32_e32 v51, v51, v59
	v_add_f32_e32 v52, v52, v60
	v_add_f32_e32 v53, v53, v61
	s_cmp_eq_u32 s42, 0
	s_cbranch_scc1 .Linp8_nof32
	global_store_dwordx4 v210, v[2:5], s[38:39] offset:0
	global_store_dwordx4 v210, v[18:21], s[38:39] offset:64
	global_store_dwordx4 v210, v[34:37], s[38:39] offset:128
	global_store_dwordx4 v210, v[50:53], s[38:39] offset:192
	s_nop 1

.Lsmp12_unit:
	s_add_u32 s20, s16, 0x5100000
	s_addc_u32 s21, s17, 0
	s_add_u32 s22, s16, 0x2100000
	s_addc_u32 s23, s17, 0
	s_add_u32 s24, s16, 0xf400000
	s_addc_u32 s25, s17, 0
	s_and_b32 s28, s12, 7
	s_lshr_b32 s29, s12, 3
	s_lshl_b32 s29, s29, 1
	s_add_u32 s29, s29, s6
	s_lshr_b32 s30, s29, 3
	s_lshl_b32 s28, s28, 3
	s_add_u32 s30, s30, s28
	s_and_b32 s31, s29, 7
	s_lshl_b32 s33, s31, 17
	s_lshl_b32 s34, s30, 17
	v_lshlrev_b32_e32 v215, 11, v202
	v_lshl_add_u32 v215, v203, 4, v215
	v_add_u32_e32 v194, s33, v204
	v_add_u32_e32 v198, s34, v215
	v_add_u32_e32 v195, s33, v204
	v_add_u32_e32 v199, s34, v215
	v_add_u32_e32 v196, s33, v204
	v_add_u32_e32 v200, s34, v215
	v_add_u32_e32 v197, s33, v204
	v_add_u32_e32 v201, s34, v215
	v_add_u32_e32 v195, 0x8000, v195
	v_add_u32_e32 v199, 0x8000, v199
	v_add_u32_e32 v196, 0x10000, v196
	v_add_u32_e32 v200, 0x10000, v200
	v_add_u32_e32 v197, 0x18000, v197
	v_add_u32_e32 v201, 0x18000, v201
	s_lshl_b32 s33, s31, 19
	s_lshl_b32 s34, s30, 7
	s_add_u32 s33, s33, s34
	v_add_u32_e32 v209, s33, v208
	s_lshl_b32 s44, s4, 8
	s_add_u32 s44, s22, s44
	s_addc_u32 s45, s23, 0
	s_lshl_b32 s46, s4, 14
	s_add_i32 m0, s46, 0x0
	s_nop 0
	global_load_lds_dwordx4 v198, s[44:45]
	s_add_i32 m0, s46, 0x400
	s_nop 0
	global_load_lds_dwordx4 v199, s[44:45]
	s_add_i32 m0, s46, 0x800
	s_nop 0
	global_load_lds_dwordx4 v200, s[44:45]
	s_add_i32 m0, s46, 0xc00
	s_nop 0
	global_load_lds_dwordx4 v201, s[44:45]
	s_add_u32 s44, s44, 64
	s_addc_u32 s45, s45, 0
	s_add_i32 m0, s46, 0x1000
	s_nop 0
	global_load_lds_dwordx4 v198, s[44:45]
	s_add_i32 m0, s46, 0x1400
	s_nop 0
	global_load_lds_dwordx4 v199, s[44:45]
	s_add_i32 m0, s46, 0x1800
	s_nop 0
	global_load_lds_dwordx4 v200, s[44:45]
	s_add_i32 m0, s46, 0x1c00
	s_nop 0
	global_load_lds_dwordx4 v201, s[44:45]
	s_add_u32 s44, s44, 64
	s_addc_u32 s45, s45, 0
	s_add_i32 m0, s46, 0x2000
	s_nop 0
	global_load_lds_dwordx4 v198, s[44:45]
	s_add_i32 m0, s46, 0x2400
	s_nop 0
	global_load_lds_dwordx4 v199, s[44:45]
	s_add_i32 m0, s46, 0x2800
	s_nop 0
	global_load_lds_dwordx4 v200, s[44:45]
	s_add_i32 m0, s46, 0x2c00
	s_nop 0
	global_load_lds_dwordx4 v201, s[44:45]
	s_add_u32 s44, s44, 64
	s_addc_u32 s45, s45, 0
	s_add_i32 m0, s46, 0x3000
	s_nop 0
	global_load_lds_dwordx4 v198, s[44:45]
	s_add_i32 m0, s46, 0x3400
	s_nop 0
	global_load_lds_dwordx4 v199, s[44:45]
	s_add_i32 m0, s46, 0x3800
	s_nop 0
	global_load_lds_dwordx4 v200, s[44:45]
	s_add_i32 m0, s46, 0x3c00
	s_nop 0
	global_load_lds_dwordx4 v201, s[44:45]
	global_load_dwordx4 v[66:69], v194, s[20:21] offset:0
	global_load_dwordx4 v[70:73], v195, s[20:21] offset:0
	global_load_dwordx4 v[74:77], v196, s[20:21] offset:0
	global_load_dwordx4 v[78:81], v197, s[20:21] offset:0
	global_load_dwordx4 v[82:85], v194, s[20:21] offset:64
	global_load_dwordx4 v[86:89], v195, s[20:21] offset:64
	global_load_dwordx4 v[90:93], v196, s[20:21] offset:64
	global_load_dwordx4 v[94:97], v197, s[20:21] offset:64
	global_load_dwordx4 v[98:101], v194, s[20:21] offset:128
	global_load_dwordx4 v[102:105], v195, s[20:21] offset:128
	global_load_dwordx4 v[106:109], v196, s[20:21] offset:128
	global_load_dwordx4 v[110:113], v197, s[20:21] offset:128
	global_load_dwordx4 v[114:117], v194, s[20:21] offset:192
	global_load_dwordx4 v[118:121], v195, s[20:21] offset:192
	global_load_dwordx4 v[122:125], v196, s[20:21] offset:192
	global_load_dwordx4 v[126:129], v197, s[20:21] offset:192
	global_load_dwordx4 v[130:133], v194, s[20:21] offset:256
	global_load_dwordx4 v[134:137], v195, s[20:21] offset:256
	global_load_dwordx4 v[138:141], v196, s[20:21] offset:256
	global_load_dwordx4 v[142:145], v197, s[20:21] offset:256
	global_load_dwordx4 v[146:149], v194, s[20:21] offset:320
	global_load_dwordx4 v[150:153], v195, s[20:21] offset:320
	global_load_dwordx4 v[154:157], v196, s[20:21] offset:320
	global_load_dwordx4 v[158:161], v197, s[20:21] offset:320
	global_load_dwordx4 v[162:165], v194, s[20:21] offset:384
	global_load_dwordx4 v[166:169], v195, s[20:21] offset:384
	global_load_dwordx4 v[170:173], v196, s[20:21] offset:384
	global_load_dwordx4 v[174:177], v197, s[20:21] offset:384
	global_load_dwordx4 v[178:181], v194, s[20:21] offset:448
	global_load_dwordx4 v[182:185], v195, s[20:21] offset:448
	global_load_dwordx4 v[186:189], v196, s[20:21] offset:448
	global_load_dwordx4 v[190:193], v197, s[20:21] offset:448
	s_waitcnt vmcnt(16)
	s_barrier
	s_lshl_b32 s47, s5, 15
	v_lshl_add_u32 v214, v205, 4, s47
	ds_read_b128 v[218:221], v214 offset:0
	ds_read_b128 v[222:225], v214 offset:1024
	ds_read_b128 v[226:229], v214 offset:2048
	ds_read_b128 v[230:233], v214 offset:3072
	ds_read_b128 v[234:237], v214 offset:4096
	ds_read_b128 v[238:241], v214 offset:5120
	ds_read_b128 v[242:245], v214 offset:6144
	ds_read_b128 v[246:249], v214 offset:7168
	s_waitcnt lgkmcnt(4)
	v_mfma_f32_16x16x32_bf16 v[2:5], v[218:221], v[66:69], 0
	v_mfma_f32_16x16x32_bf16 v[6:9], v[222:225], v[66:69], 0
	v_mfma_f32_16x16x32_bf16 v[10:13], v[226:229], v[66:69], 0
	v_mfma_f32_16x16x32_bf16 v[14:17], v[230:233], v[66:69], 0
	v_mfma_f32_16x16x32_bf16 v[18:21], v[218:221], v[70:73], 0
	v_mfma_f32_16x16x32_bf16 v[22:25], v[222:225], v[70:73], 0
	v_mfma_f32_16x16x32_bf16 v[26:29], v[226:229], v[70:73], 0
	v_mfma_f32_16x16x32_bf16 v[30:33], v[230:233], v[70:73], 0
	v_mfma_f32_16x16x32_bf16 v[34:37], v[218:221], v[74:77], 0
	v_mfma_f32_16x16x32_bf16 v[38:41], v[222:225], v[74:77], 0
	v_mfma_f32_16x16x32_bf16 v[42:45], v[226:229], v[74:77], 0
	v_mfma_f32_16x16x32_bf16 v[46:49], v[230:233], v[74:77], 0
	v_mfma_f32_16x16x32_bf16 v[50:53], v[218:221], v[78:81], 0
	v_mfma_f32_16x16x32_bf16 v[54:57], v[222:225], v[78:81], 0
	v_mfma_f32_16x16x32_bf16 v[58:61], v[226:229], v[78:81], 0
	v_mfma_f32_16x16x32_bf16 v[62:65], v[230:233], v[78:81], 0
	ds_read_b128 v[218:221], v214 offset:8192
	ds_read_b128 v[222:225], v214 offset:9216
	ds_read_b128 v[226:229], v214 offset:10240
	ds_read_b128 v[230:233], v214 offset:11264
	s_waitcnt lgkmcnt(4)
	v_mfma_f32_16x16x32_bf16 v[2:5], v[234:237], v[82:85], v[2:5]
	v_mfma_f32_16x16x32_bf16 v[6:9], v[238:241], v[82:85], v[6:9]
	v_mfma_f32_16x16x32_bf16 v[10:13], v[242:245], v[82:85], v[10:13]
	v_mfma_f32_16x16x32_bf16 v[14:17], v[246:249], v[82:85], v[14:17]
	v_mfma_f32_16x16x32_bf16 v[18:21], v[234:237], v[86:89], v[18:21]
	v_mfma_f32_16x16x32_bf16 v[22:25], v[238:241], v[86:89], v[22:25]
	v_mfma_f32_16x16x32_bf16 v[26:29], v[242:245], v[86:89], v[26:29]
	v_mfma_f32_16x16x32_bf16 v[30:33], v[246:249], v[86:89], v[30:33]
	v_mfma_f32_16x16x32_bf16 v[34:37], v[234:237], v[90:93], v[34:37]
	v_mfma_f32_16x16x32_bf16 v[38:41], v[238:241], v[90:93], v[38:41]
	v_mfma_f32_16x16x32_bf16 v[42:45], v[242:245], v[90:93], v[42:45]
	v_mfma_f32_16x16x32_bf16 v[46:49], v[246:249], v[90:93], v[46:49]
	v_mfma_f32_16x16x32_bf16 v[50:53], v[234:237], v[94:97], v[50:53]
	v_mfma_f32_16x16x32_bf16 v[54:57], v[238:241], v[94:97], v[54:57]
	v_mfma_f32_16x16x32_bf16 v[58:61], v[242:245], v[94:97], v[58:61]
	v_mfma_f32_16x16x32_bf16 v[62:65], v[246:249], v[94:97], v[62:65]
	ds_read_b128 v[234:237], v214 offset:12288
	ds_read_b128 v[238:241], v214 offset:13312
	ds_read_b128 v[242:245], v214 offset:14336
	ds_read_b128 v[246:249], v214 offset:15360
	s_waitcnt lgkmcnt(4)
	v_mfma_f32_16x16x32_bf16 v[2:5], v[218:221], v[98:101], v[2:5]
	v_mfma_f32_16x16x32_bf16 v[6:9], v[222:225], v[98:101], v[6:9]
	v_mfma_f32_16x16x32_bf16 v[10:13], v[226:229], v[98:101], v[10:13]
	v_mfma_f32_16x16x32_bf16 v[14:17], v[230:233], v[98:101], v[14:17]
	v_mfma_f32_16x16x32_bf16 v[18:21], v[218:221], v[102:105], v[18:21]
	v_mfma_f32_16x16x32_bf16 v[22:25], v[222:225], v[102:105], v[22:25]
	v_mfma_f32_16x16x32_bf16 v[26:29], v[226:229], v[102:105], v[26:29]
	v_mfma_f32_16x16x32_bf16 v[30:33], v[230:233], v[102:105], v[30:33]
	v_mfma_f32_16x16x32_bf16 v[34:37], v[218:221], v[106:109], v[34:37]
	v_mfma_f32_16x16x32_bf16 v[38:41], v[222:225], v[106:109], v[38:41]
	v_mfma_f32_16x16x32_bf16 v[42:45], v[226:229], v[106:109], v[42:45]
	v_mfma_f32_16x16x32_bf16 v[46:49], v[230:233], v[106:109], v[46:49]
	v_mfma_f32_16x16x32_bf16 v[50:53], v[218:221], v[110:113], v[50:53]
	v_mfma_f32_16x16x32_bf16 v[54:57], v[222:225], v[110:113], v[54:57]
	v_mfma_f32_16x16x32_bf16 v[58:61], v[226:229], v[110:113], v[58:61]
	v_mfma_f32_16x16x32_bf16 v[62:65], v[230:233], v[110:113], v[62:65]
	ds_read_b128 v[218:221], v214 offset:16384
	ds_read_b128 v[222:225], v214 offset:17408
	ds_read_b128 v[226:229], v214 offset:18432
	ds_read_b128 v[230:233], v214 offset:19456
	s_waitcnt lgkmcnt(4)
	v_mfma_f32_16x16x32_bf16 v[2:5], v[234:237], v[114:117], v[2:5]
	v_mfma_f32_16x16x32_bf16 v[6:9], v[238:241], v[114:117], v[6:9]
	v_mfma_f32_16x16x32_bf16 v[10:13], v[242:245], v[114:117], v[10:13]
	v_mfma_f32_16x16x32_bf16 v[14:17], v[246:249], v[114:117], v[14:17]
	v_mfma_f32_16x16x32_bf16 v[18:21], v[234:237], v[118:121], v[18:21]
	v_mfma_f32_16x16x32_bf16 v[22:25], v[238:241], v[118:121], v[22:25]
	v_mfma_f32_16x16x32_bf16 v[26:29], v[242:245], v[118:121], v[26:29]
	v_mfma_f32_16x16x32_bf16 v[30:33], v[246:249], v[118:121], v[30:33]
	v_mfma_f32_16x16x32_bf16 v[34:37], v[234:237], v[122:125], v[34:37]
	v_mfma_f32_16x16x32_bf16 v[38:41], v[238:241], v[122:125], v[38:41]
	v_mfma_f32_16x16x32_bf16 v[42:45], v[242:245], v[122:125], v[42:45]
	v_mfma_f32_16x16x32_bf16 v[46:49], v[246:249], v[122:125], v[46:49]
	v_mfma_f32_16x16x32_bf16 v[50:53], v[234:237], v[126:129], v[50:53]
	v_mfma_f32_16x16x32_bf16 v[54:57], v[238:241], v[126:129], v[54:57]
	v_mfma_f32_16x16x32_bf16 v[58:61], v[242:245], v[126:129], v[58:61]
	v_mfma_f32_16x16x32_bf16 v[62:65], v[246:249], v[126:129], v[62:65]
	s_waitcnt vmcnt(0)
	ds_read_b128 v[234:237], v214 offset:20480
	ds_read_b128 v[238:241], v214 offset:21504
	ds_read_b128 v[242:245], v214 offset:22528
	ds_read_b128 v[246:249], v214 offset:23552
	s_waitcnt lgkmcnt(4)
	v_mfma_f32_16x16x32_bf16 v[2:5], v[218:221], v[130:133], v[2:5]
	v_mfma_f32_16x16x32_bf16 v[6:9], v[222:225], v[130:133], v[6:9]
	v_mfma_f32_16x16x32_bf16 v[10:13], v[226:229], v[130:133], v[10:13]
	v_mfma_f32_16x16x32_bf16 v[14:17], v[230:233], v[130:133], v[14:17]
	v_mfma_f32_16x16x32_bf16 v[18:21], v[218:221], v[134:137], v[18:21]
	v_mfma_f32_16x16x32_bf16 v[22:25], v[222:225], v[134:137], v[22:25]
	v_mfma_f32_16x16x32_bf16 v[26:29], v[226:229], v[134:137], v[26:29]
	v_mfma_f32_16x16x32_bf16 v[30:33], v[230:233], v[134:137], v[30:33]
	v_mfma_f32_16x16x32_bf16 v[34:37], v[218:221], v[138:141], v[34:37]
	v_mfma_f32_16x16x32_bf16 v[38:41], v[222:225], v[138:141], v[38:41]
	v_mfma_f32_16x16x32_bf16 v[42:45], v[226:229], v[138:141], v[42:45]
	v_mfma_f32_16x16x32_bf16 v[46:49], v[230:233], v[138:141], v[46:49]
	v_mfma_f32_16x16x32_bf16 v[50:53], v[218:221], v[142:145], v[50:53]
	v_mfma_f32_16x16x32_bf16 v[54:57], v[222:225], v[142:145], v[54:57]
	v_mfma_f32_16x16x32_bf16 v[58:61], v[226:229], v[142:145], v[58:61]
	v_mfma_f32_16x16x32_bf16 v[62:65], v[230:233], v[142:145], v[62:65]
	ds_read_b128 v[218:221], v214 offset:24576
	ds_read_b128 v[222:225], v214 offset:25600
	ds_read_b128 v[226:229], v214 offset:26624
	ds_read_b128 v[230:233], v214 offset:27648
	s_waitcnt lgkmcnt(4)
	v_mfma_f32_16x16x32_bf16 v[2:5], v[234:237], v[146:149], v[2:5]
	v_mfma_f32_16x16x32_bf16 v[6:9], v[238:241], v[146:149], v[6:9]
	v_mfma_f32_16x16x32_bf16 v[10:13], v[242:245], v[146:149], v[10:13]
	v_mfma_f32_16x16x32_bf16 v[14:17], v[246:249], v[146:149], v[14:17]
	v_mfma_f32_16x16x32_bf16 v[18:21], v[234:237], v[150:153], v[18:21]
	v_mfma_f32_16x16x32_bf16 v[22:25], v[238:241], v[150:153], v[22:25]
	v_mfma_f32_16x16x32_bf16 v[26:29], v[242:245], v[150:153], v[26:29]
	v_mfma_f32_16x16x32_bf16 v[30:33], v[246:249], v[150:153], v[30:33]
	v_mfma_f32_16x16x32_bf16 v[34:37], v[234:237], v[154:157], v[34:37]
	v_mfma_f32_16x16x32_bf16 v[38:41], v[238:241], v[154:157], v[38:41]
	v_mfma_f32_16x16x32_bf16 v[42:45], v[242:245], v[154:157], v[42:45]
	v_mfma_f32_16x16x32_bf16 v[46:49], v[246:249], v[154:157], v[46:49]
	v_mfma_f32_16x16x32_bf16 v[50:53], v[234:237], v[158:161], v[50:53]
	v_mfma_f32_16x16x32_bf16 v[54:57], v[238:241], v[158:161], v[54:57]
	v_mfma_f32_16x16x32_bf16 v[58:61], v[242:245], v[158:161], v[58:61]
	v_mfma_f32_16x16x32_bf16 v[62:65], v[246:249], v[158:161], v[62:65]
	ds_read_b128 v[234:237], v214 offset:28672
	ds_read_b128 v[238:241], v214 offset:29696
	ds_read_b128 v[242:245], v214 offset:30720
	ds_read_b128 v[246:249], v214 offset:31744
	s_waitcnt lgkmcnt(4)
	v_mfma_f32_16x16x32_bf16 v[2:5], v[218:221], v[162:165], v[2:5]
	v_mfma_f32_16x16x32_bf16 v[6:9], v[222:225], v[162:165], v[6:9]
	v_mfma_f32_16x16x32_bf16 v[10:13], v[226:229], v[162:165], v[10:13]
	v_mfma_f32_16x16x32_bf16 v[14:17], v[230:233], v[162:165], v[14:17]
	v_mfma_f32_16x16x32_bf16 v[18:21], v[218:221], v[166:169], v[18:21]
	v_mfma_f32_16x16x32_bf16 v[22:25], v[222:225], v[166:169], v[22:25]
	v_mfma_f32_16x16x32_bf16 v[26:29], v[226:229], v[166:169], v[26:29]
	v_mfma_f32_16x16x32_bf16 v[30:33], v[230:233], v[166:169], v[30:33]
	v_mfma_f32_16x16x32_bf16 v[34:37], v[218:221], v[170:173], v[34:37]
	v_mfma_f32_16x16x32_bf16 v[38:41], v[222:225], v[170:173], v[38:41]
	v_mfma_f32_16x16x32_bf16 v[42:45], v[226:229], v[170:173], v[42:45]
	v_mfma_f32_16x16x32_bf16 v[46:49], v[230:233], v[170:173], v[46:49]
	v_mfma_f32_16x16x32_bf16 v[50:53], v[218:221], v[174:177], v[50:53]
	v_mfma_f32_16x16x32_bf16 v[54:57], v[222:225], v[174:177], v[54:57]
	v_mfma_f32_16x16x32_bf16 v[58:61], v[226:229], v[174:177], v[58:61]
	v_mfma_f32_16x16x32_bf16 v[62:65], v[230:233], v[174:177], v[62:65]
	s_waitcnt lgkmcnt(0)
	v_mfma_f32_16x16x32_bf16 v[2:5], v[234:237], v[178:181], v[2:5]
	v_mfma_f32_16x16x32_bf16 v[6:9], v[238:241], v[178:181], v[6:9]
	v_mfma_f32_16x16x32_bf16 v[10:13], v[242:245], v[178:181], v[10:13]
	v_mfma_f32_16x16x32_bf16 v[14:17], v[246:249], v[178:181], v[14:17]
	v_mfma_f32_16x16x32_bf16 v[18:21], v[234:237], v[182:185], v[18:21]
	v_mfma_f32_16x16x32_bf16 v[22:25], v[238:241], v[182:185], v[22:25]
	v_mfma_f32_16x16x32_bf16 v[26:29], v[242:245], v[182:185], v[26:29]
	v_mfma_f32_16x16x32_bf16 v[30:33], v[246:249], v[182:185], v[30:33]
	v_mfma_f32_16x16x32_bf16 v[34:37], v[234:237], v[186:189], v[34:37]
	v_mfma_f32_16x16x32_bf16 v[38:41], v[238:241], v[186:189], v[38:41]
	v_mfma_f32_16x16x32_bf16 v[42:45], v[242:245], v[186:189], v[42:45]
	v_mfma_f32_16x16x32_bf16 v[46:49], v[246:249], v[186:189], v[46:49]
	v_mfma_f32_16x16x32_bf16 v[50:53], v[234:237], v[190:193], v[50:53]
	v_mfma_f32_16x16x32_bf16 v[54:57], v[238:241], v[190:193], v[54:57]
	v_mfma_f32_16x16x32_bf16 v[58:61], v[242:245], v[190:193], v[58:61]
	v_mfma_f32_16x16x32_bf16 v[62:65], v[246:249], v[190:193], v[62:65]
	s_nop 7
	s_barrier
	ds_write_b128 v206, v[2:5] offset:0
	ds_write_b128 v206, v[6:9] offset:1024
	ds_write_b128 v206, v[10:13] offset:2048
	ds_write_b128 v206, v[14:17] offset:3072
	ds_write_b128 v206, v[18:21] offset:4096
	ds_write_b128 v206, v[22:25] offset:5120
	ds_write_b128 v206, v[26:29] offset:6144
	ds_write_b128 v206, v[30:33] offset:7168
	ds_write_b128 v206, v[34:37] offset:8192
	ds_write_b128 v206, v[38:41] offset:9216
	ds_write_b128 v206, v[42:45] offset:10240
	ds_write_b128 v206, v[46:49] offset:11264
	ds_write_b128 v206, v[50:53] offset:12288
	ds_write_b128 v206, v[54:57] offset:13312
	ds_write_b128 v206, v[58:61] offset:14336
	ds_write_b128 v206, v[62:65] offset:15360
	s_waitcnt lgkmcnt(0)
	s_barrier
	ds_read_b128 v[2:5], v207 offset:0
	ds_read_b128 v[6:9], v207 offset:16384
	ds_read_b128 v[10:13], v207 offset:32768
	ds_read_b128 v[14:17], v207 offset:49152
	ds_read_b128 v[18:21], v207 offset:1024
	ds_read_b128 v[22:25], v207 offset:17408
	ds_read_b128 v[26:29], v207 offset:33792
	ds_read_b128 v[30:33], v207 offset:50176
	ds_read_b128 v[34:37], v207 offset:2048
	ds_read_b128 v[38:41], v207 offset:18432
	ds_read_b128 v[42:45], v207 offset:34816
	ds_read_b128 v[46:49], v207 offset:51200
	ds_read_b128 v[50:53], v207 offset:3072
	ds_read_b128 v[54:57], v207 offset:19456
	ds_read_b128 v[58:61], v207 offset:35840
	ds_read_b128 v[62:65], v207 offset:52224
	s_waitcnt lgkmcnt(12)
	v_add_f32_e32 v2, v2, v6
	v_add_f32_e32 v3, v3, v7
	v_add_f32_e32 v4, v4, v8
	v_add_f32_e32 v5, v5, v9
	v_add_f32_e32 v10, v10, v14
	v_add_f32_e32 v11, v11, v15
	v_add_f32_e32 v12, v12, v16
	v_add_f32_e32 v13, v13, v17
	v_add_f32_e32 v2, v2, v10
	v_add_f32_e32 v3, v3, v11
	v_add_f32_e32 v4, v4, v12
	v_add_f32_e32 v5, v5, v13
	s_waitcnt lgkmcnt(8)
	v_add_f32_e32 v18, v18, v22
	v_add_f32_e32 v19, v19, v23
	v_add_f32_e32 v20, v20, v24
	v_add_f32_e32 v21, v21, v25
	v_add_f32_e32 v26, v26, v30
	v_add_f32_e32 v27, v27, v31
	v_add_f32_e32 v28, v28, v32
	v_add_f32_e32 v29, v29, v33
	v_add_f32_e32 v18, v18, v26
	v_add_f32_e32 v19, v19, v27
	v_add_f32_e32 v20, v20, v28
	v_add_f32_e32 v21, v21, v29
	s_waitcnt lgkmcnt(4)
	v_add_f32_e32 v34, v34, v38
	v_add_f32_e32 v35, v35, v39
	v_add_f32_e32 v36, v36, v40
	v_add_f32_e32 v37, v37, v41
	v_add_f32_e32 v42, v42, v46
	v_add_f32_e32 v43, v43, v47
	v_add_f32_e32 v44, v44, v48
	v_add_f32_e32 v45, v45, v49
	v_add_f32_e32 v34, v34, v42
	v_add_f32_e32 v35, v35, v43
	v_add_f32_e32 v36, v36, v44
	v_add_f32_e32 v37, v37, v45
	s_waitcnt lgkmcnt(0)
	v_add_f32_e32 v50, v50, v54
	v_add_f32_e32 v51, v51, v55
	v_add_f32_e32 v52, v52, v56
	v_add_f32_e32 v53, v53, v57
	v_add_f32_e32 v58, v58, v62
	v_add_f32_e32 v59, v59, v63
	v_add_f32_e32 v60, v60, v64
	v_add_f32_e32 v61, v61, v65
	v_add_f32_e32 v50, v50, v58
	v_add_f32_e32 v51, v51, v59
	v_add_f32_e32 v52, v52, v60
	v_add_f32_e32 v53, v53, v61
	v_max_f32_e32 v2, 0, v2
	v_max_f32_e32 v3, 0, v3
	v_max_f32_e32 v4, 0, v4
	v_max_f32_e32 v5, 0, v5
	v_mul_f32_e32 v2, v2, v2
	v_mul_f32_e32 v3, v3, v3
	v_mul_f32_e32 v4, v4, v4
	v_mul_f32_e32 v5, v5, v5
	v_cvt_pk_bf16_f32 v210, v2, v3
	v_cvt_pk_bf16_f32 v211, v4, v5
	global_store_dwordx2 v209, v[210:211], s[24:25] offset:0
	v_max_f32_e32 v18, 0, v18
	v_max_f32_e32 v19, 0, v19
	v_max_f32_e32 v20, 0, v20
	v_max_f32_e32 v21, 0, v21
	v_mul_f32_e32 v18, v18, v18
	v_mul_f32_e32 v19, v19, v19
	v_mul_f32_e32 v20, v20, v20
	v_mul_f32_e32 v21, v21, v21
	v_cvt_pk_bf16_f32 v212, v18, v19
	v_cvt_pk_bf16_f32 v213, v20, v21
	global_store_dwordx2 v209, v[212:213], s[24:25] offset:32
	v_max_f32_e32 v34, 0, v34
	v_max_f32_e32 v35, 0, v35
	v_max_f32_e32 v36, 0, v36
	v_max_f32_e32 v37, 0, v37
	v_mul_f32_e32 v34, v34, v34
	v_mul_f32_e32 v35, v35, v35
	v_mul_f32_e32 v36, v36, v36
	v_mul_f32_e32 v37, v37, v37
	v_cvt_pk_bf16_f32 v214, v34, v35
	v_cvt_pk_bf16_f32 v215, v36, v37
	global_store_dwordx2 v209, v[214:215], s[24:25] offset:64
	v_max_f32_e32 v50, 0, v50
	v_max_f32_e32 v51, 0, v51
	v_max_f32_e32 v52, 0, v52
	v_max_f32_e32 v53, 0, v53
	v_mul_f32_e32 v50, v50, v50
	v_mul_f32_e32 v51, v51, v51
	v_mul_f32_e32 v52, v52, v52
	v_mul_f32_e32 v53, v53, v53
	v_cvt_pk_bf16_f32 v216, v50, v51
	v_cvt_pk_bf16_f32 v217, v52, v53
	global_store_dwordx2 v209, v[216:217], s[24:25] offset:96
	s_barrier
	s_add_i32 s12, s12, s3
	s_cmpk_lt_u32 s12, 0x100
	s_cbranch_scc1 .Lsmp12_unit
